# rwkv_post_rows: previous-row loads no longer waited on before the pass's other loads are issued (unpack deferred, one round trip per pass instead of two)
# speedup vs baseline: 1.0106x; 1.0106x over previous
; __device__ __forceinline__ float lo_bf(unsigned w) { return __uint_as_float(w << 16); }
; __device__ __forceinline__ float hi_bf(unsigned w) { return __uint_as_float(w & 0xffff0000u); }
; __device__ __forceinline__ void rwkv_post_rows(const Params& P, int l, int rbeg, int rend) {
;     ...
;         bool first; const float* st = nullptr;
;         if (R < MP) first = (R & 4095) == 0;
;         else { const int rs = R - MP; first = (rs & 15) == 0; st = P.in[5] + (size_t)(l * 16 + (rs >> 4)) * SHIFT_W; }
; #pragma unroll
;         for (int hq = 0; hq < 4; ++hq) {
;             const int col = hq * 256 + lane * 4;
;             const u16* p = proj + (size_t)R * NIN + OFF_SHIFT + col;
;             const u32x2 cr = *(const u32x2*)p, ck = *(const u32x2*)(p + 1024), cv = *(const u32x2*)(p + 2048);
;             float pr[4] = {lo_bf(cr.x), hi_bf(cr.x), lo_bf(cr.y), hi_bf(cr.y)}, pk[4] = {lo_bf(ck.x), hi_bf(ck.x), lo_bf(ck.y), hi_bf(ck.y)},
;                   pv[4] = {lo_bf(cv.x), hi_bf(cv.x), lo_bf(cv.y), hi_bf(cv.y)};
;             float qr[4], qk[4], qv[4];
;             if (!first) {
;                 const u32x2 dr = *(const u32x2*)(p - NIN), dk = *(const u32x2*)(p + 1024 - NIN), dv = *(const u32x2*)(p + 2048 - NIN);
;                 qr[0] = lo_bf(dr.x); qr[1] = hi_bf(dr.x); qr[2] = lo_bf(dr.y); qr[3] = hi_bf(dr.y);
;                 qk[0] = lo_bf(dk.x); qk[1] = hi_bf(dk.x); qk[2] = lo_bf(dk.y); qk[3] = hi_bf(dk.y);
;                 qv[0] = lo_bf(dv.x); qv[1] = hi_bf(dv.x); qv[2] = lo_bf(dv.y); qv[3] = hi_bf(dv.y);
.LBB0_1873:
	s_andn2_saveexec_b64 s[2:3], s[2:3]
	v_and_b32_e32 v0, 0xfff, v25
	v_mov_b64_e32 v[58:59], 0
	s_or_b64 exec, exec, s[2:3]
	v_lshl_add_u64 v[62:63], s[74:75], 0, v[56:57]
	v_add_co_u32_e32 v2, vcc, 0xe085000, v62
	v_cmp_ne_u32_e64 s[4:5], 0, v0
	s_nop 0
	v_addc_co_u32_e32 v3, vcc, 0, v63, vcc
	v_add_co_u32_e32 v4, vcc, 0xe086000, v62
	v_cmp_ne_u64_e64 s[2:3], 0, v[58:59]
	s_nop 0
	v_addc_co_u32_e32 v5, vcc, 0, v63, vcc
	global_load_dwordx2 v[70:71], v[2:3], off offset:2048
	global_load_dwordx2 v[68:69], v[4:5], off
	global_load_dwordx2 v[60:61], v[4:5], off offset:2048
	s_and_saveexec_b64 s[18:19], s[4:5]
	s_xor_b64 s[66:67], exec, s[18:19]
	s_cbranch_execz .LBB0_1877
	v_add_co_u32_e32 v0, vcc, 0xe07e000, v62
	s_nop 1
	v_addc_co_u32_e32 v1, vcc, 0, v63, vcc
	v_add_co_u32_e32 v4, vcc, 0xe07f000, v62
	global_load_dwordx2 v[2:3], v[0:1], off offset:768
	s_nop 0
	global_load_dwordx2 v[0:1], v[0:1], off offset:2816
	v_addc_co_u32_e32 v5, vcc, 0, v63, vcc
	global_load_dwordx2 v[152:153], v[4:5], off offset:768

; __device__ __forceinline__ void rwkv_post_rows(const Params& P, int l, int rbeg, int rend) {
;     ...
;             const int col = hq * 256 + lane * 4;
;             const u16* p = proj + (size_t)R * NIN + OFF_SHIFT + col;
;             const u32x2 cr = *(const u32x2*)p, ck = *(const u32x2*)(p + 1024), cv = *(const u32x2*)(p + 2048);
;             float pr[4] = {lo_bf(cr.x), hi_bf(cr.x), lo_bf(cr.y), hi_bf(cr.y)}, pk[4] = {lo_bf(ck.x), hi_bf(ck.x), lo_bf(ck.y), hi_bf(ck.y)},
;                   pv[4] = {lo_bf(cv.x), hi_bf(cv.x), lo_bf(cv.y), hi_bf(cv.y)};
;             float qr[4], qk[4], qv[4];
;             if (!first) {
;                 const u32x2 dr = *(const u32x2*)(p - NIN), dk = *(const u32x2*)(p + 1024 - NIN), dv = *(const u32x2*)(p + 2048 - NIN);
;                 qr[0] = lo_bf(dr.x); qr[1] = hi_bf(dr.x); qr[2] = lo_bf(dr.y); qr[3] = hi_bf(dr.y);
;                 qk[0] = lo_bf(dk.x); qk[1] = hi_bf(dk.x); qk[2] = lo_bf(dk.y); qk[3] = hi_bf(dk.y);
;                 qv[0] = lo_bf(dv.x); qv[1] = hi_bf(dv.x); qv[2] = lo_bf(dv.y); qv[3] = hi_bf(dv.y);
;             } else {
; #pragma unroll
;                 for (int e = 0; e < 4; ++e) { qr[e] = st ? st[col + e] : 0.f; qk[e] = st ? st[1024 + col + e] : 0.f; qv[e] = st ? st[2048 + col + e] : 0.f; }
;             }
;             const f32x4 mr = *(const f32x4*)(mu + col), mk = *(const f32x4*)(mu + 1024 + col), mv = *(const f32x4*)(mu + 2048 + col);
;             const f32x4 a = *(const f32x4*)(aa + (size_t)R * 1024 + col);
;             const f32x4 ka = *(const f32x4*)(P.in[17] + l * 1024 + col), rk = *(const f32x4*)(P.in[18] + l * 1024 + col);
;             const f32x4 gw = *(const f32x4*)(P.in[19] + l * 1024 + col), gb = *(const f32x4*)(P.in[20] + l * 1024 + col);
;             const f32x4 y = *(const f32x4*)(yraw + (size_t)R * 1024 + col);
;             float xv[4], bon = 0.f;
; #pragma unroll
;             for (int e = 0; e < 4; ++e) {
;                 const float xr = pr[e] + (qr[e] - pr[e]) * mr[e], xk = pk[e] + (qk[e] - pk[e]) * mk[e];
;                 xv[e] = pv[e] + (qv[e] - pv[e]) * mv[e];
;                 bon += xr * (xk * (1.f + (a[e] - 1.f) * ka[e])) * rk[e];
;             }
;             bon = red16(bon);
;             const float mean = red16(y[0] + y[1] + y[2] + y[3]) * (1.f / 64.f);
;             float d[4], vs = 0.f;
; #pragma unroll
.LBB0_1897:
	s_or_b64 exec, exec, s[66:67]
	v_lshl_add_u64 v[66:67], s[74:75], 0, v[54:55]
	v_add_co_u32_e32 v64, vcc, s14, v66
	global_load_dwordx4 v[80:83], v[28:29], off
	global_load_dwordx4 v[84:87], v[30:31], off
	global_load_dwordx4 v[12:15], v[32:33], off
	v_addc_co_u32_e32 v65, vcc, 0, v67, vcc
	v_add_co_u32_e32 v66, vcc, s15, v66
	global_load_dwordx4 v[88:91], v[64:65], off
	global_load_dwordx4 v[16:19], v[50:51], off
	global_load_dwordx4 v[20:23], v[52:53], off
	v_addc_co_u32_e32 v67, vcc, 0, v67, vcc
	global_load_dwordx4 v[92:95], v[66:67], off
	global_load_dwordx4 v[96:99], v[46:47], off
	global_load_dwordx4 v[100:103], v[48:49], off
	s_waitcnt vmcnt(9)
	s_and_saveexec_b64 s[18:19], s[4:5]
	v_lshlrev_b32_e32 v4, 16, v2
	v_and_b32_e32 v5, 0xffff0000, v2
	v_lshlrev_b32_e32 v6, 16, v3
	v_and_b32_e32 v7, 0xffff0000, v3
	v_lshlrev_b32_e32 v8, 16, v0
	v_and_b32_e32 v9, 0xffff0000, v0
	v_lshlrev_b32_e32 v10, 16, v1
	v_and_b32_e32 v11, 0xffff0000, v1
	v_lshlrev_b32_e32 v0, 16, v152
	v_and_b32_e32 v1, 0xffff0000, v152
	v_lshlrev_b32_e32 v2, 16, v153
	v_and_b32_e32 v3, 0xffff0000, v153
	s_mov_b64 exec, s[18:19]
	s_waitcnt vmcnt(9)
	v_lshlrev_b32_e32 v76, 16, v60
	v_and_b32_e32 v112, 0xffff0000, v60
	v_add_co_u32_e32 v60, vcc, s17, v62
	v_lshlrev_b32_e32 v114, 16, v61
	v_and_b32_e32 v74, 0xffff0000, v61
	v_addc_co_u32_e32 v61, vcc, 0, v63, vcc
	global_load_dwordx2 v[116:117], v[60:61], off offset:1280
	v_and_b32_e32 v109, 0xffff0000, v68
	v_lshlrev_b32_e32 v108, 16, v68
	v_add_co_u32_e32 v68, vcc, 0xe085000, v62
	v_and_b32_e32 v111, 0xffff0000, v69
	v_lshlrev_b32_e32 v110, 16, v69
	v_addc_co_u32_e32 v69, vcc, 0, v63, vcc
	v_add_co_u32_e32 v120, vcc, 0xe086000, v62
	v_and_b32_e32 v105, 0xffff0000, v70
	v_lshlrev_b32_e32 v104, 16, v70
	v_and_b32_e32 v107, 0xffff0000, v71
	v_lshlrev_b32_e32 v106, 16, v71
	v_addc_co_u32_e32 v121, vcc, 0, v63, vcc
	global_load_dwordx2 v[72:73], v[68:69], off offset:2560
	global_load_dwordx2 v[70:71], v[120:121], off offset:512
	s_nop 0
	global_load_dwordx2 v[68:69], v[120:121], off offset:2560
	v_pk_add_f32 v[4:5], v[4:5], v[104:105] neg_lo:[0,1] neg_hi:[0,1]
	v_pk_add_f32 v[6:7], v[6:7], v[106:107] neg_lo:[0,1] neg_hi:[0,1]
	v_pk_add_f32 v[8:9], v[8:9], v[108:109] neg_lo:[0,1] neg_hi:[0,1]
	v_pk_add_f32 v[10:11], v[10:11], v[110:111] neg_lo:[0,1] neg_hi:[0,1]
	v_mov_b32_e32 v26, v1
	v_mov_b32_e32 v118, v76
	s_waitcnt vmcnt(12)
	v_pk_fma_f32 v[4:5], v[4:5], v[80:81], v[104:105]
	v_pk_fma_f32 v[6:7], v[6:7], v[82:83], v[106:107]
	s_waitcnt vmcnt(10)
	v_mov_b32_e32 v80, v12
	v_pk_fma_f32 v[8:9], v[8:9], v[84:85], v[108:109]
	v_pk_fma_f32 v[10:11], v[10:11], v[86:87], v[110:111]
	s_waitcnt vmcnt(9)
	v_pk_add_f32 v[82:83], v[88:89], -1.0 op_sel_hi:[1,0]
	v_pk_add_f32 v[84:85], v[90:91], -1.0 op_sel_hi:[1,0]
	s_waitcnt vmcnt(8)
	v_mov_b32_e32 v81, v16
	s_waitcnt vmcnt(6)
	v_add_f32_e32 v12, v92, v93
	s_waitcnt vmcnt(5)
	v_pk_fma_f32 v[82:83], v[82:83], v[96:97], 1.0 op_sel_hi:[1,1,0]
	v_add_f32_e32 v12, v94, v12
	v_pk_mul_f32 v[8:9], v[8:9], v[82:83]
	v_add_f32_e32 v12, v95, v12
	v_pk_fma_f32 v[84:85], v[84:85], v[98:99], 1.0 op_sel_hi:[1,1,0]
	v_pk_mul_f32 v[4:5], v[4:5], v[8:9]
	v_add_f32_dpp v8, v12, v12 quad_perm:[1,0,3,2] row_mask:0xf bank_mask:0xf bound_ctrl:1
	v_pk_mul_f32 v[10:11], v[10:11], v[84:85]
	s_waitcnt vmcnt(4)
	v_pk_mul_f32 v[4:5], v[100:101], v[4:5]
	v_add_f32_dpp v8, v8, v8 quad_perm:[2,3,0,1] row_mask:0xf bank_mask:0xf bound_ctrl:1
	v_pk_mul_f32 v[6:7], v[6:7], v[10:11]
	v_add_f32_e32 v4, 0, v4
	v_add_f32_dpp v8, v8, v8 row_half_mirror row_mask:0xf bank_mask:0xf bound_ctrl:1
	v_pk_mul_f32 v[6:7], v[102:103], v[6:7]
	v_add_f32_e32 v4, v5, v4
	v_add_f32_dpp v5, v8, v8 row_mirror row_mask:0xf bank_mask:0xf bound_ctrl:1
	v_add_f32_e32 v6, v6, v4
	v_mul_f32_e32 v4, 0x3c800000, v5
	v_add_f32_e32 v8, v7, v6
	v_pk_add_f32 v[6:7], v[92:93], v[4:5] op_sel_hi:[1,0] neg_lo:[0,1] neg_hi:[0,1]
	v_pk_add_f32 v[4:5], v[94:95], v[4:5] op_sel_hi:[1,0] neg_lo:[0,1] neg_hi:[0,1]
	v_add_f32_dpp v12, v8, v8 quad_perm:[1,0,3,2] row_mask:0xf bank_mask:0xf bound_ctrl:1
	v_pk_mul_f32 v[8:9], v[6:7], v[6:7]
	v_pk_mul_f32 v[10:11], v[4:5], v[4:5]
	v_add_f32_e32 v8, v8, v9
	v_add_f32_e32 v8, v10, v8
	v_add_f32_e32 v8, v11, v8
	v_add_f32_dpp v12, v12, v12 quad_perm:[2,3,0,1] row_mask:0xf bank_mask:0xf bound_ctrl:1
	v_mov_b32_e32 v119, v20
	v_add_f32_dpp v8, v8, v8 quad_perm:[1,0,3,2] row_mask:0xf bank_mask:0xf bound_ctrl:1
	v_mov_b32_e32 v16, v13
	s_nop 0
	v_add_f32_dpp v8, v8, v8 quad_perm:[2,3,0,1] row_mask:0xf bank_mask:0xf bound_ctrl:1
	s_nop 1
	v_add_f32_dpp v8, v8, v8 row_half_mirror row_mask:0xf bank_mask:0xf bound_ctrl:1
	s_nop 1
	v_add_f32_dpp v8, v8, v8 row_mirror row_mask:0xf bank_mask:0xf bound_ctrl:1
	v_fmamk_f32 v8, v8, 0x3c800000, v78
	v_mul_f32_e32 v9, 0x4b800000, v8
	v_cmp_gt_f32_e32 vcc, s16, v8
	s_nop 1
	v_cndmask_b32_e32 v8, v8, v9, vcc
	v_rsq_f32_e32 v8, v8
	v_add_f32_dpp v9, v12, v12 row_half_mirror row_mask:0xf bank_mask:0xf bound_ctrl:1
	s_nop 1
	v_mov_b32_dpp v10, v9 row_mirror row_mask:0xf bank_mask:0xf bound_ctrl:1
	v_add_f32_e32 v12, v9, v10
	v_mul_f32_e32 v9, 0x45800000, v8
	v_cndmask_b32_e32 v77, v8, v9, vcc
	v_pk_add_f32 v[0:1], v[0:1], v[76:77] neg_lo:[0,1] neg_hi:[0,1]
	v_pk_mul_f32 v[8:9], v[6:7], v[76:77] op_sel_hi:[0,1]
	v_mov_b32_e32 v113, v77
	v_mov_b32_e32 v1, v9
	v_pk_fma_f32 v[0:1], v[0:1], v[80:81], v[118:119]
	v_pk_add_f32 v[8:9], v[26:27], v[112:113] neg_lo:[0,1] neg_hi:[0,1]
	v_pk_mul_f32 v[6:7], v[6:7], v[112:113]
	v_fmac_f32_e32 v1, v0, v12
	v_mov_b32_e32 v9, v7
	v_mov_b32_e32 v113, v21
	v_mov_b32_e32 v115, v77
	v_mov_b32_e32 v0, v3
	v_mov_b32_e32 v75, v77
	v_pk_fma_f32 v[6:7], v[8:9], v[16:17], v[112:113]
	v_pk_add_f32 v[8:9], v[2:3], v[114:115] neg_lo:[0,1] neg_hi:[0,1]
	v_pk_mul_f32 v[10:11], v[4:5], v[114:115] op_sel_hi:[0,1]
	v_pk_add_f32 v[2:3], v[0:1], v[74:75] neg_lo:[0,1] neg_hi:[0,1]
	s_waitcnt vmcnt(3)
	v_lshlrev_b32_e32 v0, 16, v116
	v_fmac_f32_e32 v7, v6, v12
	v_mov_b32_e32 v9, v11
	v_mov_b32_e32 v10, v14
	v_mov_b32_e32 v11, v18
	v_mov_b32_e32 v115, v22
	v_pk_mul_f32 v[4:5], v[4:5], v[74:75]
	v_mul_f32_e32 v0, v1, v0
	v_and_b32_e32 v1, 0xffff0000, v116
	v_pk_fma_f32 v[8:9], v[8:9], v[10:11], v[114:115]
	v_mov_b32_e32 v3, v5
	v_mov_b32_e32 v18, v15
	v_mov_b32_e32 v75, v23
	v_mul_f32_e32 v1, v7, v1
	v_fmac_f32_e32 v9, v8, v12
	v_pk_fma_f32 v[2:3], v[2:3], v[18:19], v[74:75]
	v_cvt_pk_bf16_f32 v0, v0, v1
	v_lshlrev_b32_e32 v1, 16, v117
	v_fmac_f32_e32 v3, v2, v12
	v_mul_f32_e32 v1, v9, v1
	v_and_b32_e32 v2, 0xffff0000, v117
	v_mul_f32_e32 v2, v3, v2
	v_cvt_pk_bf16_f32 v1, v1, v2
	global_store_dwordx2 v[60:61], v[0:1], off offset:1280
	s_and_saveexec_b64 s[18:19], s[4:5]
	s_xor_b64 s[66:67], exec, s[18:19]
	s_cbranch_execz .LBB0_1899
; __device__ __forceinline__ void rwkv_post_rows(const Params& P, int l, int rbeg, int rend) {
;     ...
;             if (!first) {
;                 const u32x2 dr = *(const u32x2*)(p - NIN), dk = *(const u32x2*)(p + 1024 - NIN), dv = *(const u32x2*)(p + 2048 - NIN);
	v_add_co_u32_e32 v0, vcc, 0xe07e000, v62
	s_nop 1
	v_addc_co_u32_e32 v1, vcc, 0, v63, vcc
	v_add_co_u32_e32 v4, vcc, 0xe07f000, v62
	global_load_dwordx2 v[2:3], v[0:1], off offset:1280
	s_nop 0
	global_load_dwordx2 v[0:1], v[0:1], off offset:3328
	v_addc_co_u32_e32 v5, vcc, 0, v63, vcc
	global_load_dwordx2 v[152:153], v[4:5], off offset:1280

; __device__ __forceinline__ void rwkv_post_rows(const Params& P, int l, int rbeg, int rend) {
;     ...
;             const int col = hq * 256 + lane * 4;
;             const u16* p = proj + (size_t)R * NIN + OFF_SHIFT + col;
;             const u32x2 cr = *(const u32x2*)p, ck = *(const u32x2*)(p + 1024), cv = *(const u32x2*)(p + 2048);
;             float pr[4] = {lo_bf(cr.x), hi_bf(cr.x), lo_bf(cr.y), hi_bf(cr.y)}, pk[4] = {lo_bf(ck.x), hi_bf(ck.x), lo_bf(ck.y), hi_bf(ck.y)},
;                   pv[4] = {lo_bf(cv.x), hi_bf(cv.x), lo_bf(cv.y), hi_bf(cv.y)};
;             float qr[4], qk[4], qv[4];
;             if (!first) {
;                 const u32x2 dr = *(const u32x2*)(p - NIN), dk = *(const u32x2*)(p + 1024 - NIN), dv = *(const u32x2*)(p + 2048 - NIN);
;                 qr[0] = lo_bf(dr.x); qr[1] = hi_bf(dr.x); qr[2] = lo_bf(dr.y); qr[3] = hi_bf(dr.y);
;                 qk[0] = lo_bf(dk.x); qk[1] = hi_bf(dk.x); qk[2] = lo_bf(dk.y); qk[3] = hi_bf(dk.y);
;                 qv[0] = lo_bf(dv.x); qv[1] = hi_bf(dv.x); qv[2] = lo_bf(dv.y); qv[3] = hi_bf(dv.y);
;             } else {
; #pragma unroll
;                 for (int e = 0; e < 4; ++e) { qr[e] = st ? st[col + e] : 0.f; qk[e] = st ? st[1024 + col + e] : 0.f; qv[e] = st ? st[2048 + col + e] : 0.f; }
;             }
;             const f32x4 mr = *(const f32x4*)(mu + col), mk = *(const f32x4*)(mu + 1024 + col), mv = *(const f32x4*)(mu + 2048 + col);
;             const f32x4 a = *(const f32x4*)(aa + (size_t)R * 1024 + col);
;             const f32x4 ka = *(const f32x4*)(P.in[17] + l * 1024 + col), rk = *(const f32x4*)(P.in[18] + l * 1024 + col);
;             const f32x4 gw = *(const f32x4*)(P.in[19] + l * 1024 + col), gb = *(const f32x4*)(P.in[20] + l * 1024 + col);
;             const f32x4 y = *(const f32x4*)(yraw + (size_t)R * 1024 + col);
;             float xv[4], bon = 0.f;
; #pragma unroll
;             for (int e = 0; e < 4; ++e) {
;                 const float xr = pr[e] + (qr[e] - pr[e]) * mr[e], xk = pk[e] + (qk[e] - pk[e]) * mk[e];
;                 xv[e] = pv[e] + (qv[e] - pv[e]) * mv[e];
;                 bon += xr * (xk * (1.f + (a[e] - 1.f) * ka[e])) * rk[e];
;             }
;             bon = red16(bon);
;             const float mean = red16(y[0] + y[1] + y[2] + y[3]) * (1.f / 64.f);
;             float d[4], vs = 0.f;
; #pragma unroll
.LBB0_1919:
	s_or_b64 exec, exec, s[66:67]
	global_load_dwordx4 v[80:83], v[28:29], off offset:1024
	global_load_dwordx4 v[84:87], v[34:35], off
	global_load_dwordx4 v[88:91], v[64:65], off offset:1024
	global_load_dwordx4 v[92:95], v[66:67], off offset:1024
	global_load_dwordx4 v[16:19], v[36:37], off
	global_load_dwordx4 v[12:15], v[50:51], off offset:1024
	global_load_dwordx4 v[20:23], v[52:53], off offset:1024
	global_load_dwordx4 v[96:99], v[46:47], off offset:1024
	global_load_dwordx4 v[100:103], v[48:49], off offset:1024
	global_load_dwordx2 v[116:117], v[60:61], off offset:1792
	s_waitcnt vmcnt(10)
	s_and_saveexec_b64 s[18:19], s[4:5]
	v_lshlrev_b32_e32 v4, 16, v2
	v_and_b32_e32 v5, 0xffff0000, v2
	v_lshlrev_b32_e32 v6, 16, v3
	v_and_b32_e32 v7, 0xffff0000, v3
	v_lshlrev_b32_e32 v8, 16, v0
	v_and_b32_e32 v9, 0xffff0000, v0
	v_lshlrev_b32_e32 v10, 16, v1
	v_and_b32_e32 v11, 0xffff0000, v1
	v_lshlrev_b32_e32 v0, 16, v152
	v_and_b32_e32 v1, 0xffff0000, v152
	v_lshlrev_b32_e32 v2, 16, v153
	v_and_b32_e32 v3, 0xffff0000, v153
	s_mov_b64 exec, s[18:19]
	s_waitcnt vmcnt(11)
	v_lshlrev_b32_e32 v110, 16, v68
	v_and_b32_e32 v112, 0xffff0000, v68
	v_add_co_u32_e32 v68, vcc, 0xe085000, v62
	v_lshlrev_b32_e32 v114, 16, v69
	v_and_b32_e32 v74, 0xffff0000, v69
	v_addc_co_u32_e32 v69, vcc, 0, v63, vcc
	v_add_co_u32_e32 v120, vcc, 0xe086000, v62
	v_and_b32_e32 v77, 0xffff0000, v72
	v_lshlrev_b32_e32 v76, 16, v72
	v_and_b32_e32 v105, 0xffff0000, v73
	v_lshlrev_b32_e32 v104, 16, v73
	v_and_b32_e32 v107, 0xffff0000, v70
	v_lshlrev_b32_e32 v106, 16, v70
	v_and_b32_e32 v109, 0xffff0000, v71
	v_lshlrev_b32_e32 v108, 16, v71
	v_addc_co_u32_e32 v121, vcc, 0, v63, vcc
	global_load_dwordx2 v[72:73], v[68:69], off offset:3072
	global_load_dwordx2 v[70:71], v[120:121], off offset:1024
	s_nop 0
	global_load_dwordx2 v[68:69], v[120:121], off offset:3072
	s_waitcnt vmcnt(13)
	v_pk_add_f32 v[4:5], v[4:5], v[76:77] neg_lo:[0,1] neg_hi:[0,1]
	v_pk_add_f32 v[8:9], v[8:9], v[106:107] neg_lo:[0,1] neg_hi:[0,1]
	v_pk_add_f32 v[6:7], v[6:7], v[104:105] neg_lo:[0,1] neg_hi:[0,1]
	v_pk_add_f32 v[10:11], v[10:11], v[108:109] neg_lo:[0,1] neg_hi:[0,1]
	v_mov_b32_e32 v26, v1
	v_mov_b32_e32 v118, v110
	s_waitcnt vmcnt(12)
	v_pk_fma_f32 v[4:5], v[4:5], v[80:81], v[76:77]
	s_waitcnt vmcnt(11)
	v_pk_fma_f32 v[8:9], v[8:9], v[84:85], v[106:107]
	s_waitcnt vmcnt(10)
	v_pk_add_f32 v[76:77], v[88:89], -1.0 op_sel_hi:[1,0]
	s_waitcnt vmcnt(9)
	v_add_f32_e32 v75, v92, v93
	v_pk_fma_f32 v[6:7], v[6:7], v[82:83], v[104:105]
	s_waitcnt vmcnt(7)
	v_mov_b32_e32 v83, v12
	v_mov_b32_e32 v12, v17
	s_waitcnt vmcnt(5)
	v_pk_fma_f32 v[76:77], v[76:77], v[96:97], 1.0 op_sel_hi:[1,1,0]
	v_add_f32_e32 v17, v94, v75
	v_pk_add_f32 v[80:81], v[90:91], -1.0 op_sel_hi:[1,0]
	v_pk_mul_f32 v[8:9], v[8:9], v[76:77]
	v_add_f32_e32 v17, v95, v17
	v_pk_fma_f32 v[10:11], v[10:11], v[86:87], v[108:109]
	v_pk_fma_f32 v[80:81], v[80:81], v[98:99], 1.0 op_sel_hi:[1,1,0]
	v_pk_mul_f32 v[4:5], v[4:5], v[8:9]
	v_add_f32_dpp v8, v17, v17 quad_perm:[1,0,3,2] row_mask:0xf bank_mask:0xf bound_ctrl:1
	v_pk_mul_f32 v[10:11], v[10:11], v[80:81]
	s_waitcnt vmcnt(4)
	v_pk_mul_f32 v[4:5], v[100:101], v[4:5]
	v_add_f32_dpp v8, v8, v8 quad_perm:[2,3,0,1] row_mask:0xf bank_mask:0xf bound_ctrl:1
	v_pk_mul_f32 v[6:7], v[6:7], v[10:11]
	v_add_f32_e32 v4, 0, v4
	v_add_f32_dpp v8, v8, v8 row_half_mirror row_mask:0xf bank_mask:0xf bound_ctrl:1
	v_pk_mul_f32 v[6:7], v[102:103], v[6:7]
	v_add_f32_e32 v4, v5, v4
	v_add_f32_dpp v5, v8, v8 row_mirror row_mask:0xf bank_mask:0xf bound_ctrl:1
	v_add_f32_e32 v6, v6, v4
	v_mul_f32_e32 v4, 0x3c800000, v5
	v_add_f32_e32 v8, v7, v6
	v_pk_add_f32 v[6:7], v[92:93], v[4:5] op_sel_hi:[1,0] neg_lo:[0,1] neg_hi:[0,1]
	v_pk_add_f32 v[4:5], v[94:95], v[4:5] op_sel_hi:[1,0] neg_lo:[0,1] neg_hi:[0,1]
	v_add_f32_dpp v17, v8, v8 quad_perm:[1,0,3,2] row_mask:0xf bank_mask:0xf bound_ctrl:1
	v_pk_mul_f32 v[8:9], v[6:7], v[6:7]
	v_pk_mul_f32 v[10:11], v[4:5], v[4:5]
	v_add_f32_e32 v8, v8, v9
	v_add_f32_e32 v8, v10, v8
	v_add_f32_e32 v8, v11, v8
	v_add_f32_dpp v17, v17, v17 quad_perm:[2,3,0,1] row_mask:0xf bank_mask:0xf bound_ctrl:1
	v_mov_b32_e32 v82, v16
	v_add_f32_dpp v8, v8, v8 quad_perm:[1,0,3,2] row_mask:0xf bank_mask:0xf bound_ctrl:1
	v_mov_b32_e32 v16, v18
	v_mov_b32_e32 v119, v20
	v_add_f32_dpp v8, v8, v8 quad_perm:[2,3,0,1] row_mask:0xf bank_mask:0xf bound_ctrl:1
	s_nop 1
	v_add_f32_dpp v8, v8, v8 row_half_mirror row_mask:0xf bank_mask:0xf bound_ctrl:1
	s_nop 1
	v_add_f32_dpp v8, v8, v8 row_mirror row_mask:0xf bank_mask:0xf bound_ctrl:1
	v_fmamk_f32 v8, v8, 0x3c800000, v78
	v_mul_f32_e32 v9, 0x4b800000, v8
	v_cmp_gt_f32_e32 vcc, s16, v8
	s_nop 1
	v_cndmask_b32_e32 v8, v8, v9, vcc
	v_rsq_f32_e32 v8, v8
	v_add_f32_dpp v9, v17, v17 row_half_mirror row_mask:0xf bank_mask:0xf bound_ctrl:1
	v_mov_b32_e32 v17, v14
	v_mov_b32_e32 v14, v19
	v_mov_b32_dpp v10, v9 row_mirror row_mask:0xf bank_mask:0xf bound_ctrl:1
	v_add_f32_e32 v18, v9, v10
	v_mul_f32_e32 v9, 0x45800000, v8
	v_cndmask_b32_e32 v111, v8, v9, vcc
	v_pk_add_f32 v[0:1], v[0:1], v[110:111] neg_lo:[0,1] neg_hi:[0,1]
	v_pk_mul_f32 v[8:9], v[6:7], v[110:111] op_sel_hi:[0,1]
	v_mov_b32_e32 v113, v111
	v_mov_b32_e32 v1, v9
	v_pk_add_f32 v[8:9], v[26:27], v[112:113] neg_lo:[0,1] neg_hi:[0,1]
	v_pk_mul_f32 v[6:7], v[6:7], v[112:113]
	v_pk_fma_f32 v[0:1], v[0:1], v[82:83], v[118:119]
	v_mov_b32_e32 v115, v111
	v_mov_b32_e32 v113, v21
	v_mov_b32_e32 v9, v7
	v_fmac_f32_e32 v1, v0, v18
	v_mov_b32_e32 v0, v3
	v_mov_b32_e32 v75, v111
	v_pk_add_f32 v[10:11], v[2:3], v[114:115] neg_lo:[0,1] neg_hi:[0,1]
	v_pk_mul_f32 v[20:21], v[4:5], v[114:115] op_sel_hi:[0,1]
	v_pk_fma_f32 v[6:7], v[8:9], v[12:13], v[112:113]
	v_pk_add_f32 v[2:3], v[0:1], v[74:75] neg_lo:[0,1] neg_hi:[0,1]
	s_waitcnt vmcnt(3)
	v_lshlrev_b32_e32 v0, 16, v116
	v_mov_b32_e32 v11, v21
	v_fmac_f32_e32 v7, v6, v18
	v_mov_b32_e32 v115, v22
	v_pk_mul_f32 v[4:5], v[4:5], v[74:75]
	v_mul_f32_e32 v0, v1, v0
	v_and_b32_e32 v1, 0xffff0000, v116
	v_pk_fma_f32 v[8:9], v[10:11], v[16:17], v[114:115]
	v_mov_b32_e32 v3, v5
	v_mov_b32_e32 v75, v23
	v_mul_f32_e32 v1, v7, v1
	v_fmac_f32_e32 v9, v8, v18
	v_pk_fma_f32 v[2:3], v[2:3], v[14:15], v[74:75]
	v_cvt_pk_bf16_f32 v0, v0, v1
	v_lshlrev_b32_e32 v1, 16, v117
	v_fmac_f32_e32 v3, v2, v18
	v_mul_f32_e32 v1, v9, v1
	v_and_b32_e32 v2, 0xffff0000, v117
	v_mul_f32_e32 v2, v3, v2
	v_cvt_pk_bf16_f32 v1, v1, v2
	global_store_dwordx2 v[60:61], v[0:1], off offset:1792
	s_and_saveexec_b64 s[18:19], s[4:5]
	s_xor_b64 s[66:67], exec, s[18:19]
	s_cbranch_execz .LBB0_1921
	v_add_co_u32_e32 v0, vcc, 0xe07e000, v62
	s_nop 1
	v_addc_co_u32_e32 v1, vcc, 0, v63, vcc
	v_add_co_u32_e32 v4, vcc, 0xe07f000, v62
	global_load_dwordx2 v[2:3], v[0:1], off offset:1792
	s_nop 0
	global_load_dwordx2 v[0:1], v[0:1], off offset:3840
	v_addc_co_u32_e32 v5, vcc, 0, v63, vcc
	global_load_dwordx2 v[152:153], v[4:5], off offset:1792

; __device__ __forceinline__ void rwkv_post_rows(const Params& P, int l, int rbeg, int rend) {
;     ...
;             const int col = hq * 256 + lane * 4;
;             const u16* p = proj + (size_t)R * NIN + OFF_SHIFT + col;
;             const u32x2 cr = *(const u32x2*)p, ck = *(const u32x2*)(p + 1024), cv = *(const u32x2*)(p + 2048);
;             float pr[4] = {lo_bf(cr.x), hi_bf(cr.x), lo_bf(cr.y), hi_bf(cr.y)}, pk[4] = {lo_bf(ck.x), hi_bf(ck.x), lo_bf(ck.y), hi_bf(ck.y)},
;                   pv[4] = {lo_bf(cv.x), hi_bf(cv.x), lo_bf(cv.y), hi_bf(cv.y)};
;             float qr[4], qk[4], qv[4];
;             if (!first) {
;                 const u32x2 dr = *(const u32x2*)(p - NIN), dk = *(const u32x2*)(p + 1024 - NIN), dv = *(const u32x2*)(p + 2048 - NIN);
;                 qr[0] = lo_bf(dr.x); qr[1] = hi_bf(dr.x); qr[2] = lo_bf(dr.y); qr[3] = hi_bf(dr.y);
;                 qk[0] = lo_bf(dk.x); qk[1] = hi_bf(dk.x); qk[2] = lo_bf(dk.y); qk[3] = hi_bf(dk.y);
;                 qv[0] = lo_bf(dv.x); qv[1] = hi_bf(dv.x); qv[2] = lo_bf(dv.y); qv[3] = hi_bf(dv.y);
;             } else {
; #pragma unroll
;                 for (int e = 0; e < 4; ++e) { qr[e] = st ? st[col + e] : 0.f; qk[e] = st ? st[1024 + col + e] : 0.f; qv[e] = st ? st[2048 + col + e] : 0.f; }
;             }
;             const f32x4 mr = *(const f32x4*)(mu + col), mk = *(const f32x4*)(mu + 1024 + col), mv = *(const f32x4*)(mu + 2048 + col);
;             const f32x4 a = *(const f32x4*)(aa + (size_t)R * 1024 + col);
;             const f32x4 ka = *(const f32x4*)(P.in[17] + l * 1024 + col), rk = *(const f32x4*)(P.in[18] + l * 1024 + col);
;             const f32x4 gw = *(const f32x4*)(P.in[19] + l * 1024 + col), gb = *(const f32x4*)(P.in[20] + l * 1024 + col);
;             const f32x4 y = *(const f32x4*)(yraw + (size_t)R * 1024 + col);
;             float xv[4], bon = 0.f;
; #pragma unroll
;             for (int e = 0; e < 4; ++e) {
;                 const float xr = pr[e] + (qr[e] - pr[e]) * mr[e], xk = pk[e] + (qk[e] - pk[e]) * mk[e];
;                 xv[e] = pv[e] + (qv[e] - pv[e]) * mv[e];
;                 bon += xr * (xk * (1.f + (a[e] - 1.f) * ka[e])) * rk[e];
;             }
;             bon = red16(bon);
;             const float mean = red16(y[0] + y[1] + y[2] + y[3]) * (1.f / 64.f);
;             float d[4], vs = 0.f;
; #pragma unroll
.LBB0_1941:
	s_or_b64 exec, exec, s[66:67]
	global_load_dwordx4 v[80:83], v[28:29], off offset:2048
	global_load_dwordx4 v[84:87], v[38:39], off
	global_load_dwordx4 v[88:91], v[64:65], off offset:2048
	global_load_dwordx4 v[92:95], v[66:67], off offset:2048
	global_load_dwordx4 v[16:19], v[40:41], off
	global_load_dwordx4 v[12:15], v[50:51], off offset:2048
	global_load_dwordx4 v[20:23], v[52:53], off offset:2048
	global_load_dwordx4 v[96:99], v[46:47], off offset:2048
	global_load_dwordx4 v[100:103], v[48:49], off offset:2048
	global_load_dwordx2 v[116:117], v[60:61], off offset:2304
	s_waitcnt vmcnt(10)
	s_and_saveexec_b64 s[18:19], s[4:5]
	v_lshlrev_b32_e32 v4, 16, v2
	v_and_b32_e32 v5, 0xffff0000, v2
	v_lshlrev_b32_e32 v6, 16, v3
	v_and_b32_e32 v7, 0xffff0000, v3
	v_lshlrev_b32_e32 v8, 16, v0
	v_and_b32_e32 v9, 0xffff0000, v0
	v_lshlrev_b32_e32 v10, 16, v1
	v_and_b32_e32 v11, 0xffff0000, v1
	v_lshlrev_b32_e32 v0, 16, v152
	v_and_b32_e32 v1, 0xffff0000, v152
	v_lshlrev_b32_e32 v2, 16, v153
	v_and_b32_e32 v3, 0xffff0000, v153
	s_mov_b64 exec, s[18:19]
	s_waitcnt vmcnt(11)
	v_lshlrev_b32_e32 v110, 16, v68
	v_and_b32_e32 v112, 0xffff0000, v68
	v_add_co_u32_e32 v68, vcc, 0xe085000, v62
	v_lshlrev_b32_e32 v114, 16, v69
	v_and_b32_e32 v74, 0xffff0000, v69
	v_addc_co_u32_e32 v69, vcc, 0, v63, vcc
	v_add_co_u32_e32 v120, vcc, 0xe086000, v62
	v_and_b32_e32 v77, 0xffff0000, v72
	v_lshlrev_b32_e32 v76, 16, v72
	v_and_b32_e32 v105, 0xffff0000, v73
	v_lshlrev_b32_e32 v104, 16, v73
	v_and_b32_e32 v107, 0xffff0000, v70
	v_lshlrev_b32_e32 v106, 16, v70
	v_and_b32_e32 v109, 0xffff0000, v71
	v_lshlrev_b32_e32 v108, 16, v71
	v_addc_co_u32_e32 v121, vcc, 0, v63, vcc
	global_load_dwordx2 v[72:73], v[68:69], off offset:3584
	global_load_dwordx2 v[70:71], v[120:121], off offset:1536
	s_nop 0
	global_load_dwordx2 v[68:69], v[120:121], off offset:3584
	s_waitcnt vmcnt(13)
	v_pk_add_f32 v[4:5], v[4:5], v[76:77] neg_lo:[0,1] neg_hi:[0,1]
	v_pk_add_f32 v[8:9], v[8:9], v[106:107] neg_lo:[0,1] neg_hi:[0,1]
	v_pk_add_f32 v[6:7], v[6:7], v[104:105] neg_lo:[0,1] neg_hi:[0,1]
	v_pk_add_f32 v[10:11], v[10:11], v[108:109] neg_lo:[0,1] neg_hi:[0,1]
	v_mov_b32_e32 v26, v1
	v_mov_b32_e32 v118, v110
	s_waitcnt vmcnt(12)
	v_pk_fma_f32 v[4:5], v[4:5], v[80:81], v[76:77]
	s_waitcnt vmcnt(11)
	v_pk_fma_f32 v[8:9], v[8:9], v[84:85], v[106:107]
	s_waitcnt vmcnt(10)
	v_pk_add_f32 v[76:77], v[88:89], -1.0 op_sel_hi:[1,0]
	s_waitcnt vmcnt(9)
	v_add_f32_e32 v75, v92, v93
	v_pk_fma_f32 v[6:7], v[6:7], v[82:83], v[104:105]
	s_waitcnt vmcnt(7)
	v_mov_b32_e32 v83, v12
	v_mov_b32_e32 v12, v17
	s_waitcnt vmcnt(5)
	v_pk_fma_f32 v[76:77], v[76:77], v[96:97], 1.0 op_sel_hi:[1,1,0]
	v_add_f32_e32 v17, v94, v75
	v_pk_add_f32 v[80:81], v[90:91], -1.0 op_sel_hi:[1,0]
	v_pk_mul_f32 v[8:9], v[8:9], v[76:77]
	v_add_f32_e32 v17, v95, v17
	v_pk_fma_f32 v[10:11], v[10:11], v[86:87], v[108:109]
	v_pk_fma_f32 v[80:81], v[80:81], v[98:99], 1.0 op_sel_hi:[1,1,0]
	v_pk_mul_f32 v[4:5], v[4:5], v[8:9]
	v_add_f32_dpp v8, v17, v17 quad_perm:[1,0,3,2] row_mask:0xf bank_mask:0xf bound_ctrl:1
	v_pk_mul_f32 v[10:11], v[10:11], v[80:81]
	s_waitcnt vmcnt(4)
	v_pk_mul_f32 v[4:5], v[100:101], v[4:5]
	v_add_f32_dpp v8, v8, v8 quad_perm:[2,3,0,1] row_mask:0xf bank_mask:0xf bound_ctrl:1
	v_pk_mul_f32 v[6:7], v[6:7], v[10:11]
	v_add_f32_e32 v4, 0, v4
	v_add_f32_dpp v8, v8, v8 row_half_mirror row_mask:0xf bank_mask:0xf bound_ctrl:1
	v_pk_mul_f32 v[6:7], v[102:103], v[6:7]
	v_add_f32_e32 v4, v5, v4
	v_add_f32_dpp v5, v8, v8 row_mirror row_mask:0xf bank_mask:0xf bound_ctrl:1
	v_add_f32_e32 v6, v6, v4
	v_mul_f32_e32 v4, 0x3c800000, v5
	v_add_f32_e32 v8, v7, v6
	v_pk_add_f32 v[6:7], v[92:93], v[4:5] op_sel_hi:[1,0] neg_lo:[0,1] neg_hi:[0,1]
	v_pk_add_f32 v[4:5], v[94:95], v[4:5] op_sel_hi:[1,0] neg_lo:[0,1] neg_hi:[0,1]
	v_add_f32_dpp v17, v8, v8 quad_perm:[1,0,3,2] row_mask:0xf bank_mask:0xf bound_ctrl:1
	v_pk_mul_f32 v[8:9], v[6:7], v[6:7]
	v_pk_mul_f32 v[10:11], v[4:5], v[4:5]
	v_add_f32_e32 v8, v8, v9
	v_add_f32_e32 v8, v10, v8
	v_add_f32_e32 v8, v11, v8
	v_add_f32_dpp v17, v17, v17 quad_perm:[2,3,0,1] row_mask:0xf bank_mask:0xf bound_ctrl:1
	v_mov_b32_e32 v82, v16
	v_add_f32_dpp v8, v8, v8 quad_perm:[1,0,3,2] row_mask:0xf bank_mask:0xf bound_ctrl:1
	v_mov_b32_e32 v16, v18
	v_mov_b32_e32 v119, v20
	v_add_f32_dpp v8, v8, v8 quad_perm:[2,3,0,1] row_mask:0xf bank_mask:0xf bound_ctrl:1
	s_nop 1
	v_add_f32_dpp v8, v8, v8 row_half_mirror row_mask:0xf bank_mask:0xf bound_ctrl:1
	s_nop 1
	v_add_f32_dpp v8, v8, v8 row_mirror row_mask:0xf bank_mask:0xf bound_ctrl:1
	v_fmamk_f32 v8, v8, 0x3c800000, v78
	v_mul_f32_e32 v9, 0x4b800000, v8
	v_cmp_gt_f32_e32 vcc, s16, v8
	s_nop 1
	v_cndmask_b32_e32 v8, v8, v9, vcc
	v_rsq_f32_e32 v8, v8
	v_add_f32_dpp v9, v17, v17 row_half_mirror row_mask:0xf bank_mask:0xf bound_ctrl:1
	v_mov_b32_e32 v17, v14
	v_mov_b32_e32 v14, v19
	v_mov_b32_dpp v10, v9 row_mirror row_mask:0xf bank_mask:0xf bound_ctrl:1
	v_add_f32_e32 v18, v9, v10
	v_mul_f32_e32 v9, 0x45800000, v8
	v_cndmask_b32_e32 v111, v8, v9, vcc
	v_pk_add_f32 v[0:1], v[0:1], v[110:111] neg_lo:[0,1] neg_hi:[0,1]
	v_pk_mul_f32 v[8:9], v[6:7], v[110:111] op_sel_hi:[0,1]
	v_mov_b32_e32 v113, v111
	v_mov_b32_e32 v1, v9
	v_pk_add_f32 v[8:9], v[26:27], v[112:113] neg_lo:[0,1] neg_hi:[0,1]
	v_pk_mul_f32 v[6:7], v[6:7], v[112:113]
	v_pk_fma_f32 v[0:1], v[0:1], v[82:83], v[118:119]
	v_mov_b32_e32 v115, v111
	v_mov_b32_e32 v113, v21
	v_mov_b32_e32 v9, v7
	v_fmac_f32_e32 v1, v0, v18
	v_mov_b32_e32 v0, v3
	v_mov_b32_e32 v75, v111
	v_pk_add_f32 v[10:11], v[2:3], v[114:115] neg_lo:[0,1] neg_hi:[0,1]
	v_pk_mul_f32 v[20:21], v[4:5], v[114:115] op_sel_hi:[0,1]
	v_pk_fma_f32 v[6:7], v[8:9], v[12:13], v[112:113]
	v_pk_add_f32 v[2:3], v[0:1], v[74:75] neg_lo:[0,1] neg_hi:[0,1]
	s_waitcnt vmcnt(3)
	v_lshlrev_b32_e32 v0, 16, v116
	v_mov_b32_e32 v11, v21
	v_fmac_f32_e32 v7, v6, v18
	v_mov_b32_e32 v115, v22
	v_pk_mul_f32 v[4:5], v[4:5], v[74:75]
	v_mul_f32_e32 v0, v1, v0
	v_and_b32_e32 v1, 0xffff0000, v116
	v_pk_fma_f32 v[8:9], v[10:11], v[16:17], v[114:115]
	v_mov_b32_e32 v3, v5
	v_mov_b32_e32 v75, v23
	v_mul_f32_e32 v1, v7, v1
	v_fmac_f32_e32 v9, v8, v18
	v_pk_fma_f32 v[2:3], v[2:3], v[14:15], v[74:75]
	v_cvt_pk_bf16_f32 v0, v0, v1
	v_lshlrev_b32_e32 v1, 16, v117
	v_fmac_f32_e32 v3, v2, v18
	v_mul_f32_e32 v1, v9, v1
	v_and_b32_e32 v2, 0xffff0000, v117
	v_mul_f32_e32 v2, v3, v2
	v_cvt_pk_bf16_f32 v1, v1, v2
	global_store_dwordx2 v[60:61], v[0:1], off offset:2304
	s_and_saveexec_b64 s[18:19], s[4:5]
	s_xor_b64 s[4:5], exec, s[18:19]
	s_cbranch_execz .LBB0_1943
; __device__ __forceinline__ float lo_bf(unsigned w) { return __uint_as_float(w << 16); }
; __device__ __forceinline__ float hi_bf(unsigned w) { return __uint_as_float(w & 0xffff0000u); }
; __device__ __forceinline__ void rwkv_post_rows(const Params& P, int l, int rbeg, int rend) {
;     ...
;             if (!first) {
;                 const u32x2 dr = *(const u32x2*)(p - NIN), dk = *(const u32x2*)(p + 1024 - NIN), dv = *(const u32x2*)(p + 2048 - NIN);
;                 qr[0] = lo_bf(dr.x); qr[1] = hi_bf(dr.x); qr[2] = lo_bf(dr.y); qr[3] = hi_bf(dr.y);
;                 qk[0] = lo_bf(dk.x); qk[1] = hi_bf(dk.x); qk[2] = lo_bf(dk.y); qk[3] = hi_bf(dk.y);
;                 qv[0] = lo_bf(dv.x); qv[1] = hi_bf(dv.x); qv[2] = lo_bf(dv.y); qv[3] = hi_bf(dv.y);
	v_add_co_u32_e32 v0, vcc, 0xe07e000, v62
	s_nop 1
	v_addc_co_u32_e32 v1, vcc, 0, v63, vcc
	v_add_co_u32_e32 v2, vcc, 0xe07f000, v62
	global_load_dwordx2 v[0:1], v[0:1], off offset:2304
	s_nop 0
	v_addc_co_u32_e32 v3, vcc, 0, v63, vcc
	global_load_dwordx2 v[10:11], v[2:3], off offset:256
	s_nop 0
	global_load_dwordx2 v[2:3], v[2:3], off offset:2304
	s_waitcnt vmcnt(2)
	v_lshlrev_b32_e32 v4, 16, v0
	v_and_b32_e32 v5, 0xffff0000, v0
	v_lshlrev_b32_e32 v6, 16, v1
	v_and_b32_e32 v7, 0xffff0000, v1
	s_waitcnt vmcnt(1)
	v_lshlrev_b32_e32 v8, 16, v10
	v_and_b32_e32 v9, 0xffff0000, v10
	v_lshlrev_b32_e32 v10, 16, v11
	v_and_b32_e32 v11, 0xffff0000, v11
	s_waitcnt vmcnt(0)
	v_lshlrev_b32_e32 v0, 16, v2
	v_and_b32_e32 v1, 0xffff0000, v2
	v_lshlrev_b32_e32 v2, 16, v3
	v_and_b32_e32 v3, 0xffff0000, v3

; __device__ __forceinline__ float lo_bf(unsigned w) { return __uint_as_float(w << 16); }
; __device__ __forceinline__ float hi_bf(unsigned w) { return __uint_as_float(w & 0xffff0000u); }
; __device__ __forceinline__ void rwkv_post_rows(const Params& P, int l, int rbeg, int rend) {
;     ...
;         bool first; const float* st = nullptr;
;         if (R < MP) first = (R & 4095) == 0;
;         else { const int rs = R - MP; first = (rs & 15) == 0; st = P.in[5] + (size_t)(l * 16 + (rs >> 4)) * SHIFT_W; }
; #pragma unroll
;         for (int hq = 0; hq < 4; ++hq) {
;             const int col = hq * 256 + lane * 4;
;             const u16* p = proj + (size_t)R * NIN + OFF_SHIFT + col;
;             const u32x2 cr = *(const u32x2*)p, ck = *(const u32x2*)(p + 1024), cv = *(const u32x2*)(p + 2048);
;             float pr[4] = {lo_bf(cr.x), hi_bf(cr.x), lo_bf(cr.y), hi_bf(cr.y)}, pk[4] = {lo_bf(ck.x), hi_bf(ck.x), lo_bf(ck.y), hi_bf(ck.y)},
;                   pv[4] = {lo_bf(cv.x), hi_bf(cv.x), lo_bf(cv.y), hi_bf(cv.y)};
;             float qr[4], qk[4], qv[4];
;             if (!first) {
;                 const u32x2 dr = *(const u32x2*)(p - NIN), dk = *(const u32x2*)(p + 1024 - NIN), dv = *(const u32x2*)(p + 2048 - NIN);
.LBB0_4178:
	v_cmp_lt_i32_e32 vcc, s14, v25
	s_and_saveexec_b64 s[0:1], vcc
	v_readlane_b32 s36, v252, 21
	s_xor_b64 s[0:1], exec, s[0:1]
	v_readlane_b32 s46, v252, 31
	v_readlane_b32 s47, v252, 32
	v_readlane_b32 s37, v252, 22
	v_readlane_b32 s38, v252, 23
	v_readlane_b32 s39, v252, 24
	v_readlane_b32 s40, v252, 25
	v_readlane_b32 s41, v252, 26
	v_readlane_b32 s42, v252, 27
	v_readlane_b32 s43, v252, 28
	v_readlane_b32 s44, v252, 29
	v_readlane_b32 s45, v252, 30
	v_readlane_b32 s48, v252, 33
	v_readlane_b32 s49, v252, 34
	v_readlane_b32 s50, v252, 35
	v_readlane_b32 s51, v252, 36
	v_add_u32_e32 v1, 0xffffc000, v25
	v_lshrrev_b32_e32 v1, 4, v1
	v_add_u32_e32 v1, 16, v1
	v_mov_b64_e32 v[2:3], s[46:47]
	v_and_b32_e32 v0, 15, v25
	v_mad_u64_u32 v[88:89], s[4:5], v1, s15, v[2:3]
	s_andn2_saveexec_b64 s[0:1], s[0:1]
	v_and_b32_e32 v0, 0xfff, v25
	v_mov_b64_e32 v[88:89], 0
	s_or_b64 exec, exec, s[0:1]
	v_lshl_add_u64 v[92:93], s[74:75], 0, v[86:87]
	v_add_co_u32_e32 v2, vcc, 0xe085000, v92
	v_cmp_ne_u32_e64 s[6:7], 0, v0
	s_nop 0
	v_addc_co_u32_e32 v3, vcc, 0, v93, vcc
	v_add_co_u32_e32 v4, vcc, 0xe086000, v92
	v_cmp_ne_u64_e64 s[0:1], 0, v[88:89]
	s_nop 0
	v_addc_co_u32_e32 v5, vcc, 0, v93, vcc
	global_load_dwordx2 v[100:101], v[2:3], off offset:2048
	global_load_dwordx2 v[98:99], v[4:5], off
	global_load_dwordx2 v[90:91], v[4:5], off offset:2048
	s_and_saveexec_b64 s[4:5], s[6:7]
	s_xor_b64 s[20:21], exec, s[4:5]
	s_cbranch_execz .LBB0_4184
	v_add_co_u32_e32 v0, vcc, 0xe07e000, v92
	s_nop 1
	v_addc_co_u32_e32 v1, vcc, 0, v93, vcc
	global_load_dwordx2 v[2:3], v[0:1], off offset:768
	global_load_dwordx2 v[10:11], v[0:1], off offset:2816
	v_add_co_u32_e32 v0, vcc, 0xe07f000, v92
	v_addc_co_u32_e32 v1, vcc, 0, v93, vcc
	global_load_dwordx2 v[152:153], v[0:1], off offset:768

; __device__ __forceinline__ void rwkv_post_rows(const Params& P, int l, int rbeg, int rend) {
;     ...
;             const int col = hq * 256 + lane * 4;
;             const u16* p = proj + (size_t)R * NIN + OFF_SHIFT + col;
;             const u32x2 cr = *(const u32x2*)p, ck = *(const u32x2*)(p + 1024), cv = *(const u32x2*)(p + 2048);
;             float pr[4] = {lo_bf(cr.x), hi_bf(cr.x), lo_bf(cr.y), hi_bf(cr.y)}, pk[4] = {lo_bf(ck.x), hi_bf(ck.x), lo_bf(ck.y), hi_bf(ck.y)},
;                   pv[4] = {lo_bf(cv.x), hi_bf(cv.x), lo_bf(cv.y), hi_bf(cv.y)};
;             float qr[4], qk[4], qv[4];
;             if (!first) {
;                 const u32x2 dr = *(const u32x2*)(p - NIN), dk = *(const u32x2*)(p + 1024 - NIN), dv = *(const u32x2*)(p + 2048 - NIN);
;                 qr[0] = lo_bf(dr.x); qr[1] = hi_bf(dr.x); qr[2] = lo_bf(dr.y); qr[3] = hi_bf(dr.y);
;                 qk[0] = lo_bf(dk.x); qk[1] = hi_bf(dk.x); qk[2] = lo_bf(dk.y); qk[3] = hi_bf(dk.y);
;                 qv[0] = lo_bf(dv.x); qv[1] = hi_bf(dv.x); qv[2] = lo_bf(dv.y); qv[3] = hi_bf(dv.y);
;             } else {
; #pragma unroll
;                 for (int e = 0; e < 4; ++e) { qr[e] = st ? st[col + e] : 0.f; qk[e] = st ? st[1024 + col + e] : 0.f; qv[e] = st ? st[2048 + col + e] : 0.f; }
;             }
;             const f32x4 mr = *(const f32x4*)(mu + col), mk = *(const f32x4*)(mu + 1024 + col), mv = *(const f32x4*)(mu + 2048 + col);
;             const f32x4 a = *(const f32x4*)(aa + (size_t)R * 1024 + col);
;             const f32x4 ka = *(const f32x4*)(P.in[17] + l * 1024 + col), rk = *(const f32x4*)(P.in[18] + l * 1024 + col);
;             const f32x4 gw = *(const f32x4*)(P.in[19] + l * 1024 + col), gb = *(const f32x4*)(P.in[20] + l * 1024 + col);
;             const f32x4 y = *(const f32x4*)(yraw + (size_t)R * 1024 + col);
;             float xv[4], bon = 0.f;
; #pragma unroll
;             for (int e = 0; e < 4; ++e) {
;                 const float xr = pr[e] + (qr[e] - pr[e]) * mr[e], xk = pk[e] + (qk[e] - pk[e]) * mk[e];
;                 xv[e] = pv[e] + (qv[e] - pv[e]) * mv[e];
;                 bon += xr * (xk * (1.f + (a[e] - 1.f) * ka[e])) * rk[e];
;             }
;             bon = red16(bon);
;             const float mean = red16(y[0] + y[1] + y[2] + y[3]) * (1.f / 64.f);
;             float d[4], vs = 0.f;
; #pragma unroll
.LBB0_4204:
	s_or_b64 exec, exec, s[20:21]
	v_lshl_add_u64 v[96:97], s[74:75], 0, v[84:85]
	v_add_co_u32_e32 v94, vcc, s24, v96
	global_load_dwordx4 v[110:113], v[28:29], off
	global_load_dwordx4 v[114:117], v[30:31], off
	global_load_dwordx4 v[12:15], v[32:33], off
	v_addc_co_u32_e32 v95, vcc, 0, v97, vcc
	v_add_co_u32_e32 v96, vcc, s25, v96
	global_load_dwordx4 v[118:121], v[94:95], off
	global_load_dwordx4 v[16:19], v[56:57], off
	global_load_dwordx4 v[20:23], v[58:59], off
	v_addc_co_u32_e32 v97, vcc, 0, v97, vcc
	global_load_dwordx4 v[122:125], v[96:97], off
	global_load_dwordx4 v[126:129], v[52:53], off
	global_load_dwordx4 v[130:133], v[54:55], off
	s_waitcnt vmcnt(9)
	s_and_saveexec_b64 s[4:5], s[6:7]
	v_lshlrev_b32_e32 v4, 16, v2
	v_and_b32_e32 v5, 0xffff0000, v2
	v_lshlrev_b32_e32 v6, 16, v3
	v_and_b32_e32 v7, 0xffff0000, v3
	v_lshlrev_b32_e32 v8, 16, v10
	v_and_b32_e32 v9, 0xffff0000, v10
	v_lshlrev_b32_e32 v10, 16, v11
	v_and_b32_e32 v11, 0xffff0000, v11
	v_lshlrev_b32_e32 v0, 16, v152
	v_and_b32_e32 v1, 0xffff0000, v152
	v_lshlrev_b32_e32 v2, 16, v153
	v_and_b32_e32 v3, 0xffff0000, v153
	s_mov_b64 exec, s[4:5]
	s_waitcnt vmcnt(9)
	v_lshlrev_b32_e32 v106, 16, v90
	v_and_b32_e32 v142, 0xffff0000, v90
	v_add_co_u32_e32 v90, vcc, s27, v92
	v_lshlrev_b32_e32 v144, 16, v91
	v_and_b32_e32 v104, 0xffff0000, v91
	v_addc_co_u32_e32 v91, vcc, 0, v93, vcc
	global_load_dwordx2 v[146:147], v[90:91], off offset:1280
	v_and_b32_e32 v139, 0xffff0000, v98
	v_lshlrev_b32_e32 v138, 16, v98
	v_add_co_u32_e32 v98, vcc, 0xe085000, v92
	v_and_b32_e32 v141, 0xffff0000, v99
	v_lshlrev_b32_e32 v140, 16, v99
	v_addc_co_u32_e32 v99, vcc, 0, v93, vcc
	v_add_co_u32_e32 v150, vcc, 0xe086000, v92
	v_and_b32_e32 v135, 0xffff0000, v100
	v_lshlrev_b32_e32 v134, 16, v100
	v_and_b32_e32 v137, 0xffff0000, v101
	v_lshlrev_b32_e32 v136, 16, v101
	v_addc_co_u32_e32 v151, vcc, 0, v93, vcc
	global_load_dwordx2 v[102:103], v[98:99], off offset:2560
	global_load_dwordx2 v[100:101], v[150:151], off offset:512
	s_nop 0
	global_load_dwordx2 v[98:99], v[150:151], off offset:2560
	v_pk_add_f32 v[4:5], v[4:5], v[134:135] neg_lo:[0,1] neg_hi:[0,1]
	v_pk_add_f32 v[6:7], v[6:7], v[136:137] neg_lo:[0,1] neg_hi:[0,1]
	v_pk_add_f32 v[8:9], v[8:9], v[138:139] neg_lo:[0,1] neg_hi:[0,1]
	v_pk_add_f32 v[10:11], v[10:11], v[140:141] neg_lo:[0,1] neg_hi:[0,1]
	v_mov_b32_e32 v26, v1
	v_mov_b32_e32 v148, v106
	s_waitcnt vmcnt(12)
	v_pk_fma_f32 v[4:5], v[4:5], v[110:111], v[134:135]
	v_pk_fma_f32 v[6:7], v[6:7], v[112:113], v[136:137]
	s_waitcnt vmcnt(10)
	v_mov_b32_e32 v110, v12
	v_pk_fma_f32 v[8:9], v[8:9], v[114:115], v[138:139]
	v_pk_fma_f32 v[10:11], v[10:11], v[116:117], v[140:141]
	s_waitcnt vmcnt(9)
	v_pk_add_f32 v[112:113], v[118:119], -1.0 op_sel_hi:[1,0]
	v_pk_add_f32 v[114:115], v[120:121], -1.0 op_sel_hi:[1,0]
	s_waitcnt vmcnt(8)
	v_mov_b32_e32 v111, v16
	s_waitcnt vmcnt(6)
	v_add_f32_e32 v12, v122, v123
	s_waitcnt vmcnt(5)
	v_pk_fma_f32 v[112:113], v[112:113], v[126:127], 1.0 op_sel_hi:[1,1,0]
	v_add_f32_e32 v12, v124, v12
	v_pk_mul_f32 v[8:9], v[8:9], v[112:113]
	v_add_f32_e32 v12, v125, v12
	v_pk_fma_f32 v[114:115], v[114:115], v[128:129], 1.0 op_sel_hi:[1,1,0]
	v_pk_mul_f32 v[4:5], v[4:5], v[8:9]
	v_add_f32_dpp v8, v12, v12 quad_perm:[1,0,3,2] row_mask:0xf bank_mask:0xf bound_ctrl:1
	v_pk_mul_f32 v[10:11], v[10:11], v[114:115]
	s_waitcnt vmcnt(4)
	v_pk_mul_f32 v[4:5], v[130:131], v[4:5]
	v_add_f32_dpp v8, v8, v8 quad_perm:[2,3,0,1] row_mask:0xf bank_mask:0xf bound_ctrl:1
	v_pk_mul_f32 v[6:7], v[6:7], v[10:11]
	v_add_f32_e32 v4, 0, v4
	v_add_f32_dpp v8, v8, v8 row_half_mirror row_mask:0xf bank_mask:0xf bound_ctrl:1
	v_pk_mul_f32 v[6:7], v[132:133], v[6:7]
	v_add_f32_e32 v4, v5, v4
	v_add_f32_dpp v5, v8, v8 row_mirror row_mask:0xf bank_mask:0xf bound_ctrl:1
	v_add_f32_e32 v6, v6, v4
	v_mul_f32_e32 v4, 0x3c800000, v5
	v_add_f32_e32 v8, v7, v6
	v_pk_add_f32 v[6:7], v[122:123], v[4:5] op_sel_hi:[1,0] neg_lo:[0,1] neg_hi:[0,1]
	v_pk_add_f32 v[4:5], v[124:125], v[4:5] op_sel_hi:[1,0] neg_lo:[0,1] neg_hi:[0,1]
	v_add_f32_dpp v12, v8, v8 quad_perm:[1,0,3,2] row_mask:0xf bank_mask:0xf bound_ctrl:1
	v_pk_mul_f32 v[8:9], v[6:7], v[6:7]
	v_pk_mul_f32 v[10:11], v[4:5], v[4:5]
	v_add_f32_e32 v8, v8, v9
	v_add_f32_e32 v8, v10, v8
	v_add_f32_e32 v8, v11, v8
	v_add_f32_dpp v12, v12, v12 quad_perm:[2,3,0,1] row_mask:0xf bank_mask:0xf bound_ctrl:1
	v_mov_b32_e32 v149, v20
	v_add_f32_dpp v8, v8, v8 quad_perm:[1,0,3,2] row_mask:0xf bank_mask:0xf bound_ctrl:1
	v_mov_b32_e32 v16, v13
	s_nop 0
	v_add_f32_dpp v8, v8, v8 quad_perm:[2,3,0,1] row_mask:0xf bank_mask:0xf bound_ctrl:1
	s_nop 1
	v_add_f32_dpp v8, v8, v8 row_half_mirror row_mask:0xf bank_mask:0xf bound_ctrl:1
	s_nop 1
	v_add_f32_dpp v8, v8, v8 row_mirror row_mask:0xf bank_mask:0xf bound_ctrl:1
	v_fmamk_f32 v8, v8, 0x3c800000, v108
	v_mul_f32_e32 v9, 0x4b800000, v8
	v_cmp_gt_f32_e32 vcc, s26, v8
	s_nop 1
	v_cndmask_b32_e32 v8, v8, v9, vcc
	v_rsq_f32_e32 v8, v8
	v_add_f32_dpp v9, v12, v12 row_half_mirror row_mask:0xf bank_mask:0xf bound_ctrl:1
	s_nop 1
	v_mov_b32_dpp v10, v9 row_mirror row_mask:0xf bank_mask:0xf bound_ctrl:1
	v_add_f32_e32 v12, v9, v10
	v_mul_f32_e32 v9, 0x45800000, v8
	v_cndmask_b32_e32 v107, v8, v9, vcc
	v_pk_add_f32 v[0:1], v[0:1], v[106:107] neg_lo:[0,1] neg_hi:[0,1]
	v_pk_mul_f32 v[8:9], v[6:7], v[106:107] op_sel_hi:[0,1]
	v_mov_b32_e32 v143, v107
	v_mov_b32_e32 v1, v9
	v_pk_fma_f32 v[0:1], v[0:1], v[110:111], v[148:149]
	v_pk_add_f32 v[8:9], v[26:27], v[142:143] neg_lo:[0,1] neg_hi:[0,1]
	v_pk_mul_f32 v[6:7], v[6:7], v[142:143]
	v_fmac_f32_e32 v1, v0, v12
	v_mov_b32_e32 v9, v7
	v_mov_b32_e32 v143, v21
	v_mov_b32_e32 v145, v107
	v_mov_b32_e32 v0, v3
	v_mov_b32_e32 v105, v107
	v_pk_fma_f32 v[6:7], v[8:9], v[16:17], v[142:143]
	v_pk_add_f32 v[8:9], v[2:3], v[144:145] neg_lo:[0,1] neg_hi:[0,1]
	v_pk_mul_f32 v[10:11], v[4:5], v[144:145] op_sel_hi:[0,1]
	v_pk_add_f32 v[2:3], v[0:1], v[104:105] neg_lo:[0,1] neg_hi:[0,1]
	s_waitcnt vmcnt(3)
	v_lshlrev_b32_e32 v0, 16, v146
	v_fmac_f32_e32 v7, v6, v12
	v_mov_b32_e32 v9, v11
	v_mov_b32_e32 v10, v14
	v_mov_b32_e32 v11, v18
	v_mov_b32_e32 v145, v22
	v_pk_mul_f32 v[4:5], v[4:5], v[104:105]
	v_mul_f32_e32 v0, v1, v0
	v_and_b32_e32 v1, 0xffff0000, v146
	v_pk_fma_f32 v[8:9], v[8:9], v[10:11], v[144:145]
	v_mov_b32_e32 v3, v5
	v_mov_b32_e32 v18, v15
	v_mov_b32_e32 v105, v23
	v_mul_f32_e32 v1, v7, v1
	v_fmac_f32_e32 v9, v8, v12
	v_pk_fma_f32 v[2:3], v[2:3], v[18:19], v[104:105]
	v_cvt_pk_bf16_f32 v0, v0, v1
	v_lshlrev_b32_e32 v1, 16, v147
	v_fmac_f32_e32 v3, v2, v12
	v_mul_f32_e32 v1, v9, v1
	v_and_b32_e32 v2, 0xffff0000, v147
	v_mul_f32_e32 v2, v3, v2
	v_cvt_pk_bf16_f32 v1, v1, v2
	global_store_dwordx2 v[90:91], v[0:1], off offset:1280
	s_and_saveexec_b64 s[4:5], s[6:7]
	s_xor_b64 s[20:21], exec, s[4:5]
	s_cbranch_execz .LBB0_4206
; __device__ __forceinline__ void rwkv_post_rows(const Params& P, int l, int rbeg, int rend) {
;     ...
;             if (!first) {
;                 const u32x2 dr = *(const u32x2*)(p - NIN), dk = *(const u32x2*)(p + 1024 - NIN), dv = *(const u32x2*)(p + 2048 - NIN);
	v_add_co_u32_e32 v0, vcc, 0xe07e000, v92
	s_nop 1
	v_addc_co_u32_e32 v1, vcc, 0, v93, vcc
	global_load_dwordx2 v[2:3], v[0:1], off offset:1280
	global_load_dwordx2 v[10:11], v[0:1], off offset:3328
	v_add_co_u32_e32 v0, vcc, 0xe07f000, v92
	v_addc_co_u32_e32 v1, vcc, 0, v93, vcc
	global_load_dwordx2 v[152:153], v[0:1], off offset:1280

; __device__ __forceinline__ void rwkv_post_rows(const Params& P, int l, int rbeg, int rend) {
;     ...
;             const int col = hq * 256 + lane * 4;
;             const u16* p = proj + (size_t)R * NIN + OFF_SHIFT + col;
;             const u32x2 cr = *(const u32x2*)p, ck = *(const u32x2*)(p + 1024), cv = *(const u32x2*)(p + 2048);
;             float pr[4] = {lo_bf(cr.x), hi_bf(cr.x), lo_bf(cr.y), hi_bf(cr.y)}, pk[4] = {lo_bf(ck.x), hi_bf(ck.x), lo_bf(ck.y), hi_bf(ck.y)},
;                   pv[4] = {lo_bf(cv.x), hi_bf(cv.x), lo_bf(cv.y), hi_bf(cv.y)};
;             float qr[4], qk[4], qv[4];
;             if (!first) {
;                 const u32x2 dr = *(const u32x2*)(p - NIN), dk = *(const u32x2*)(p + 1024 - NIN), dv = *(const u32x2*)(p + 2048 - NIN);
;                 qr[0] = lo_bf(dr.x); qr[1] = hi_bf(dr.x); qr[2] = lo_bf(dr.y); qr[3] = hi_bf(dr.y);
;                 qk[0] = lo_bf(dk.x); qk[1] = hi_bf(dk.x); qk[2] = lo_bf(dk.y); qk[3] = hi_bf(dk.y);
;                 qv[0] = lo_bf(dv.x); qv[1] = hi_bf(dv.x); qv[2] = lo_bf(dv.y); qv[3] = hi_bf(dv.y);
;             } else {
; #pragma unroll
;                 for (int e = 0; e < 4; ++e) { qr[e] = st ? st[col + e] : 0.f; qk[e] = st ? st[1024 + col + e] : 0.f; qv[e] = st ? st[2048 + col + e] : 0.f; }
;             }
;             const f32x4 mr = *(const f32x4*)(mu + col), mk = *(const f32x4*)(mu + 1024 + col), mv = *(const f32x4*)(mu + 2048 + col);
;             const f32x4 a = *(const f32x4*)(aa + (size_t)R * 1024 + col);
;             const f32x4 ka = *(const f32x4*)(P.in[17] + l * 1024 + col), rk = *(const f32x4*)(P.in[18] + l * 1024 + col);
;             const f32x4 gw = *(const f32x4*)(P.in[19] + l * 1024 + col), gb = *(const f32x4*)(P.in[20] + l * 1024 + col);
;             const f32x4 y = *(const f32x4*)(yraw + (size_t)R * 1024 + col);
;             float xv[4], bon = 0.f;
; #pragma unroll
;             for (int e = 0; e < 4; ++e) {
;                 const float xr = pr[e] + (qr[e] - pr[e]) * mr[e], xk = pk[e] + (qk[e] - pk[e]) * mk[e];
;                 xv[e] = pv[e] + (qv[e] - pv[e]) * mv[e];
;                 bon += xr * (xk * (1.f + (a[e] - 1.f) * ka[e])) * rk[e];
;             }
;             bon = red16(bon);
;             const float mean = red16(y[0] + y[1] + y[2] + y[3]) * (1.f / 64.f);
;             float d[4], vs = 0.f;
; #pragma unroll
.LBB0_4226:
	s_or_b64 exec, exec, s[20:21]
	global_load_dwordx4 v[110:113], v[34:35], off
	global_load_dwordx4 v[114:117], v[36:37], off
	global_load_dwordx4 v[118:121], v[94:95], off offset:1024
	global_load_dwordx4 v[122:125], v[96:97], off offset:1024
	global_load_dwordx4 v[16:19], v[38:39], off
	global_load_dwordx4 v[12:15], v[64:65], off
	global_load_dwordx4 v[20:23], v[66:67], off
	global_load_dwordx4 v[126:129], v[60:61], off
	global_load_dwordx4 v[130:133], v[62:63], off
	global_load_dwordx2 v[146:147], v[90:91], off offset:1792
	s_waitcnt vmcnt(10)
	s_and_saveexec_b64 s[4:5], s[6:7]
	v_lshlrev_b32_e32 v4, 16, v2
	v_and_b32_e32 v5, 0xffff0000, v2
	v_lshlrev_b32_e32 v6, 16, v3
	v_and_b32_e32 v7, 0xffff0000, v3
	v_lshlrev_b32_e32 v8, 16, v10
	v_and_b32_e32 v9, 0xffff0000, v10
	v_lshlrev_b32_e32 v10, 16, v11
	v_and_b32_e32 v11, 0xffff0000, v11
	v_lshlrev_b32_e32 v0, 16, v152
	v_and_b32_e32 v1, 0xffff0000, v152
	v_lshlrev_b32_e32 v2, 16, v153
	v_and_b32_e32 v3, 0xffff0000, v153
	s_mov_b64 exec, s[4:5]
	s_waitcnt vmcnt(11)
	v_lshlrev_b32_e32 v140, 16, v98
	v_and_b32_e32 v142, 0xffff0000, v98
	v_add_co_u32_e32 v98, vcc, 0xe085000, v92
	v_lshlrev_b32_e32 v144, 16, v99
	v_and_b32_e32 v104, 0xffff0000, v99
	v_addc_co_u32_e32 v99, vcc, 0, v93, vcc
	v_add_co_u32_e32 v150, vcc, 0xe086000, v92
	v_and_b32_e32 v107, 0xffff0000, v102
	v_lshlrev_b32_e32 v106, 16, v102
	v_and_b32_e32 v135, 0xffff0000, v103
	v_lshlrev_b32_e32 v134, 16, v103
	v_and_b32_e32 v137, 0xffff0000, v100
	v_lshlrev_b32_e32 v136, 16, v100
	v_and_b32_e32 v139, 0xffff0000, v101
	v_lshlrev_b32_e32 v138, 16, v101
	v_addc_co_u32_e32 v151, vcc, 0, v93, vcc
	global_load_dwordx2 v[102:103], v[98:99], off offset:3072
	global_load_dwordx2 v[100:101], v[150:151], off offset:1024
	s_nop 0
	global_load_dwordx2 v[98:99], v[150:151], off offset:3072
	s_waitcnt vmcnt(13)
	v_pk_add_f32 v[4:5], v[4:5], v[106:107] neg_lo:[0,1] neg_hi:[0,1]
	v_pk_add_f32 v[8:9], v[8:9], v[136:137] neg_lo:[0,1] neg_hi:[0,1]
	v_pk_add_f32 v[6:7], v[6:7], v[134:135] neg_lo:[0,1] neg_hi:[0,1]
	v_pk_add_f32 v[10:11], v[10:11], v[138:139] neg_lo:[0,1] neg_hi:[0,1]
	v_mov_b32_e32 v26, v1
	v_mov_b32_e32 v148, v140
	s_waitcnt vmcnt(12)
	v_pk_fma_f32 v[4:5], v[4:5], v[110:111], v[106:107]
	s_waitcnt vmcnt(11)
	v_pk_fma_f32 v[8:9], v[8:9], v[114:115], v[136:137]
	s_waitcnt vmcnt(10)
	v_pk_add_f32 v[106:107], v[118:119], -1.0 op_sel_hi:[1,0]
	s_waitcnt vmcnt(9)
	v_add_f32_e32 v105, v122, v123
	v_pk_fma_f32 v[6:7], v[6:7], v[112:113], v[134:135]
	s_waitcnt vmcnt(7)
	v_mov_b32_e32 v113, v12
	v_mov_b32_e32 v12, v17
	s_waitcnt vmcnt(5)
	v_pk_fma_f32 v[106:107], v[106:107], v[126:127], 1.0 op_sel_hi:[1,1,0]
	v_add_f32_e32 v17, v124, v105
	v_pk_add_f32 v[110:111], v[120:121], -1.0 op_sel_hi:[1,0]
	v_pk_mul_f32 v[8:9], v[8:9], v[106:107]
	v_add_f32_e32 v17, v125, v17
	v_pk_fma_f32 v[10:11], v[10:11], v[116:117], v[138:139]
	v_pk_fma_f32 v[110:111], v[110:111], v[128:129], 1.0 op_sel_hi:[1,1,0]
	v_pk_mul_f32 v[4:5], v[4:5], v[8:9]
	v_add_f32_dpp v8, v17, v17 quad_perm:[1,0,3,2] row_mask:0xf bank_mask:0xf bound_ctrl:1
	v_pk_mul_f32 v[10:11], v[10:11], v[110:111]
	s_waitcnt vmcnt(4)
	v_pk_mul_f32 v[4:5], v[130:131], v[4:5]
	v_add_f32_dpp v8, v8, v8 quad_perm:[2,3,0,1] row_mask:0xf bank_mask:0xf bound_ctrl:1
	v_pk_mul_f32 v[6:7], v[6:7], v[10:11]
	v_add_f32_e32 v4, 0, v4
	v_add_f32_dpp v8, v8, v8 row_half_mirror row_mask:0xf bank_mask:0xf bound_ctrl:1
	v_pk_mul_f32 v[6:7], v[132:133], v[6:7]
	v_add_f32_e32 v4, v5, v4
	v_add_f32_dpp v5, v8, v8 row_mirror row_mask:0xf bank_mask:0xf bound_ctrl:1
	v_add_f32_e32 v6, v6, v4
	v_mul_f32_e32 v4, 0x3c800000, v5
	v_add_f32_e32 v8, v7, v6
	v_pk_add_f32 v[6:7], v[122:123], v[4:5] op_sel_hi:[1,0] neg_lo:[0,1] neg_hi:[0,1]
	v_pk_add_f32 v[4:5], v[124:125], v[4:5] op_sel_hi:[1,0] neg_lo:[0,1] neg_hi:[0,1]
	v_add_f32_dpp v17, v8, v8 quad_perm:[1,0,3,2] row_mask:0xf bank_mask:0xf bound_ctrl:1
	v_pk_mul_f32 v[8:9], v[6:7], v[6:7]
	v_pk_mul_f32 v[10:11], v[4:5], v[4:5]
	v_add_f32_e32 v8, v8, v9
	v_add_f32_e32 v8, v10, v8
	v_add_f32_e32 v8, v11, v8
	v_add_f32_dpp v17, v17, v17 quad_perm:[2,3,0,1] row_mask:0xf bank_mask:0xf bound_ctrl:1
	v_mov_b32_e32 v112, v16
	v_add_f32_dpp v8, v8, v8 quad_perm:[1,0,3,2] row_mask:0xf bank_mask:0xf bound_ctrl:1
	v_mov_b32_e32 v16, v18
	v_mov_b32_e32 v149, v20
	v_add_f32_dpp v8, v8, v8 quad_perm:[2,3,0,1] row_mask:0xf bank_mask:0xf bound_ctrl:1
	s_nop 1
	v_add_f32_dpp v8, v8, v8 row_half_mirror row_mask:0xf bank_mask:0xf bound_ctrl:1
	s_nop 1
	v_add_f32_dpp v8, v8, v8 row_mirror row_mask:0xf bank_mask:0xf bound_ctrl:1
	v_fmamk_f32 v8, v8, 0x3c800000, v108
	v_mul_f32_e32 v9, 0x4b800000, v8
	v_cmp_gt_f32_e32 vcc, s26, v8
	s_nop 1
	v_cndmask_b32_e32 v8, v8, v9, vcc
	v_rsq_f32_e32 v8, v8
	v_add_f32_dpp v9, v17, v17 row_half_mirror row_mask:0xf bank_mask:0xf bound_ctrl:1
	v_mov_b32_e32 v17, v14
	v_mov_b32_e32 v14, v19
	v_mov_b32_dpp v10, v9 row_mirror row_mask:0xf bank_mask:0xf bound_ctrl:1
	v_add_f32_e32 v18, v9, v10
	v_mul_f32_e32 v9, 0x45800000, v8
	v_cndmask_b32_e32 v141, v8, v9, vcc
	v_pk_add_f32 v[0:1], v[0:1], v[140:141] neg_lo:[0,1] neg_hi:[0,1]
	v_pk_mul_f32 v[8:9], v[6:7], v[140:141] op_sel_hi:[0,1]
	v_mov_b32_e32 v143, v141
	v_mov_b32_e32 v1, v9
	v_pk_add_f32 v[8:9], v[26:27], v[142:143] neg_lo:[0,1] neg_hi:[0,1]
	v_pk_mul_f32 v[6:7], v[6:7], v[142:143]
	v_pk_fma_f32 v[0:1], v[0:1], v[112:113], v[148:149]
	v_mov_b32_e32 v145, v141
	v_mov_b32_e32 v143, v21
	v_mov_b32_e32 v9, v7
	v_fmac_f32_e32 v1, v0, v18
	v_mov_b32_e32 v0, v3
	v_mov_b32_e32 v105, v141
	v_pk_add_f32 v[10:11], v[2:3], v[144:145] neg_lo:[0,1] neg_hi:[0,1]
	v_pk_mul_f32 v[20:21], v[4:5], v[144:145] op_sel_hi:[0,1]
	v_pk_fma_f32 v[6:7], v[8:9], v[12:13], v[142:143]
	v_pk_add_f32 v[2:3], v[0:1], v[104:105] neg_lo:[0,1] neg_hi:[0,1]
	s_waitcnt vmcnt(3)
	v_lshlrev_b32_e32 v0, 16, v146
	v_mov_b32_e32 v11, v21
	v_fmac_f32_e32 v7, v6, v18
	v_mov_b32_e32 v145, v22
	v_pk_mul_f32 v[4:5], v[4:5], v[104:105]
	v_mul_f32_e32 v0, v1, v0
	v_and_b32_e32 v1, 0xffff0000, v146
	v_pk_fma_f32 v[8:9], v[10:11], v[16:17], v[144:145]
	v_mov_b32_e32 v3, v5
	v_mov_b32_e32 v105, v23
	v_mul_f32_e32 v1, v7, v1
	v_fmac_f32_e32 v9, v8, v18
	v_pk_fma_f32 v[2:3], v[2:3], v[14:15], v[104:105]
	v_cvt_pk_bf16_f32 v0, v0, v1
	v_lshlrev_b32_e32 v1, 16, v147
	v_fmac_f32_e32 v3, v2, v18
	v_mul_f32_e32 v1, v9, v1
	v_and_b32_e32 v2, 0xffff0000, v147
	v_mul_f32_e32 v2, v3, v2
	v_cvt_pk_bf16_f32 v1, v1, v2
	global_store_dwordx2 v[90:91], v[0:1], off offset:1792
	s_and_saveexec_b64 s[4:5], s[6:7]
	s_xor_b64 s[20:21], exec, s[4:5]
	s_cbranch_execz .LBB0_4228
	v_add_co_u32_e32 v0, vcc, 0xe07e000, v92
	s_nop 1
	v_addc_co_u32_e32 v1, vcc, 0, v93, vcc
	global_load_dwordx2 v[2:3], v[0:1], off offset:1792
	global_load_dwordx2 v[10:11], v[0:1], off offset:3840
	v_add_co_u32_e32 v0, vcc, 0xe07f000, v92
	v_addc_co_u32_e32 v1, vcc, 0, v93, vcc
	global_load_dwordx2 v[152:153], v[0:1], off offset:1792

; __device__ __forceinline__ void rwkv_post_rows(const Params& P, int l, int rbeg, int rend) {
;     ...
;             const int col = hq * 256 + lane * 4;
;             const u16* p = proj + (size_t)R * NIN + OFF_SHIFT + col;
;             const u32x2 cr = *(const u32x2*)p, ck = *(const u32x2*)(p + 1024), cv = *(const u32x2*)(p + 2048);
;             float pr[4] = {lo_bf(cr.x), hi_bf(cr.x), lo_bf(cr.y), hi_bf(cr.y)}, pk[4] = {lo_bf(ck.x), hi_bf(ck.x), lo_bf(ck.y), hi_bf(ck.y)},
;                   pv[4] = {lo_bf(cv.x), hi_bf(cv.x), lo_bf(cv.y), hi_bf(cv.y)};
;             float qr[4], qk[4], qv[4];
;             if (!first) {
;                 const u32x2 dr = *(const u32x2*)(p - NIN), dk = *(const u32x2*)(p + 1024 - NIN), dv = *(const u32x2*)(p + 2048 - NIN);
;                 qr[0] = lo_bf(dr.x); qr[1] = hi_bf(dr.x); qr[2] = lo_bf(dr.y); qr[3] = hi_bf(dr.y);
;                 qk[0] = lo_bf(dk.x); qk[1] = hi_bf(dk.x); qk[2] = lo_bf(dk.y); qk[3] = hi_bf(dk.y);
;                 qv[0] = lo_bf(dv.x); qv[1] = hi_bf(dv.x); qv[2] = lo_bf(dv.y); qv[3] = hi_bf(dv.y);
;             } else {
; #pragma unroll
;                 for (int e = 0; e < 4; ++e) { qr[e] = st ? st[col + e] : 0.f; qk[e] = st ? st[1024 + col + e] : 0.f; qv[e] = st ? st[2048 + col + e] : 0.f; }
;             }
;             const f32x4 mr = *(const f32x4*)(mu + col), mk = *(const f32x4*)(mu + 1024 + col), mv = *(const f32x4*)(mu + 2048 + col);
;             const f32x4 a = *(const f32x4*)(aa + (size_t)R * 1024 + col);
;             const f32x4 ka = *(const f32x4*)(P.in[17] + l * 1024 + col), rk = *(const f32x4*)(P.in[18] + l * 1024 + col);
;             const f32x4 gw = *(const f32x4*)(P.in[19] + l * 1024 + col), gb = *(const f32x4*)(P.in[20] + l * 1024 + col);
;             const f32x4 y = *(const f32x4*)(yraw + (size_t)R * 1024 + col);
;             float xv[4], bon = 0.f;
; #pragma unroll
;             for (int e = 0; e < 4; ++e) {
;                 const float xr = pr[e] + (qr[e] - pr[e]) * mr[e], xk = pk[e] + (qk[e] - pk[e]) * mk[e];
;                 xv[e] = pv[e] + (qv[e] - pv[e]) * mv[e];
;                 bon += xr * (xk * (1.f + (a[e] - 1.f) * ka[e])) * rk[e];
;             }
;             bon = red16(bon);
;             const float mean = red16(y[0] + y[1] + y[2] + y[3]) * (1.f / 64.f);
;             float d[4], vs = 0.f;
; #pragma unroll
.LBB0_4248:
	s_or_b64 exec, exec, s[20:21]
	global_load_dwordx4 v[110:113], v[40:41], off
	global_load_dwordx4 v[114:117], v[42:43], off
	global_load_dwordx4 v[118:121], v[94:95], off offset:2048
	global_load_dwordx4 v[122:125], v[96:97], off offset:2048
	global_load_dwordx4 v[16:19], v[44:45], off
	global_load_dwordx4 v[12:15], v[72:73], off
	global_load_dwordx4 v[20:23], v[74:75], off
	global_load_dwordx4 v[126:129], v[68:69], off
	global_load_dwordx4 v[130:133], v[70:71], off
	global_load_dwordx2 v[146:147], v[90:91], off offset:2304
	s_waitcnt vmcnt(10)
	s_and_saveexec_b64 s[4:5], s[6:7]
	v_lshlrev_b32_e32 v4, 16, v2
	v_and_b32_e32 v5, 0xffff0000, v2
	v_lshlrev_b32_e32 v6, 16, v3
	v_and_b32_e32 v7, 0xffff0000, v3
	v_lshlrev_b32_e32 v8, 16, v10
	v_and_b32_e32 v9, 0xffff0000, v10
	v_lshlrev_b32_e32 v10, 16, v11
	v_and_b32_e32 v11, 0xffff0000, v11
	v_lshlrev_b32_e32 v0, 16, v152
	v_and_b32_e32 v1, 0xffff0000, v152
	v_lshlrev_b32_e32 v2, 16, v153
	v_and_b32_e32 v3, 0xffff0000, v153
	s_mov_b64 exec, s[4:5]
	s_waitcnt vmcnt(11)
	v_lshlrev_b32_e32 v140, 16, v98
	v_and_b32_e32 v142, 0xffff0000, v98
	v_add_co_u32_e32 v98, vcc, 0xe085000, v92
	v_lshlrev_b32_e32 v144, 16, v99
	v_and_b32_e32 v104, 0xffff0000, v99
	v_addc_co_u32_e32 v99, vcc, 0, v93, vcc
	v_add_co_u32_e32 v150, vcc, 0xe086000, v92
	v_and_b32_e32 v107, 0xffff0000, v102
	v_lshlrev_b32_e32 v106, 16, v102
	v_and_b32_e32 v135, 0xffff0000, v103
	v_lshlrev_b32_e32 v134, 16, v103
	v_and_b32_e32 v137, 0xffff0000, v100
	v_lshlrev_b32_e32 v136, 16, v100
	v_and_b32_e32 v139, 0xffff0000, v101
	v_lshlrev_b32_e32 v138, 16, v101
	v_addc_co_u32_e32 v151, vcc, 0, v93, vcc
	global_load_dwordx2 v[102:103], v[98:99], off offset:3584
	global_load_dwordx2 v[100:101], v[150:151], off offset:1536
	s_nop 0
	global_load_dwordx2 v[98:99], v[150:151], off offset:3584
	s_waitcnt vmcnt(13)
	v_pk_add_f32 v[4:5], v[4:5], v[106:107] neg_lo:[0,1] neg_hi:[0,1]
	v_pk_add_f32 v[8:9], v[8:9], v[136:137] neg_lo:[0,1] neg_hi:[0,1]
	v_pk_add_f32 v[6:7], v[6:7], v[134:135] neg_lo:[0,1] neg_hi:[0,1]
	v_pk_add_f32 v[10:11], v[10:11], v[138:139] neg_lo:[0,1] neg_hi:[0,1]
	v_mov_b32_e32 v26, v1
	v_mov_b32_e32 v148, v140
	s_waitcnt vmcnt(12)
	v_pk_fma_f32 v[4:5], v[4:5], v[110:111], v[106:107]
	s_waitcnt vmcnt(11)
	v_pk_fma_f32 v[8:9], v[8:9], v[114:115], v[136:137]
	s_waitcnt vmcnt(10)
	v_pk_add_f32 v[106:107], v[118:119], -1.0 op_sel_hi:[1,0]
	s_waitcnt vmcnt(9)
	v_add_f32_e32 v105, v122, v123
	v_pk_fma_f32 v[6:7], v[6:7], v[112:113], v[134:135]
	s_waitcnt vmcnt(7)
	v_mov_b32_e32 v113, v12
	v_mov_b32_e32 v12, v17
	s_waitcnt vmcnt(5)
	v_pk_fma_f32 v[106:107], v[106:107], v[126:127], 1.0 op_sel_hi:[1,1,0]
	v_add_f32_e32 v17, v124, v105
	v_pk_add_f32 v[110:111], v[120:121], -1.0 op_sel_hi:[1,0]
	v_pk_mul_f32 v[8:9], v[8:9], v[106:107]
	v_add_f32_e32 v17, v125, v17
	v_pk_fma_f32 v[10:11], v[10:11], v[116:117], v[138:139]
	v_pk_fma_f32 v[110:111], v[110:111], v[128:129], 1.0 op_sel_hi:[1,1,0]
	v_pk_mul_f32 v[4:5], v[4:5], v[8:9]
	v_add_f32_dpp v8, v17, v17 quad_perm:[1,0,3,2] row_mask:0xf bank_mask:0xf bound_ctrl:1
	v_pk_mul_f32 v[10:11], v[10:11], v[110:111]
	s_waitcnt vmcnt(4)
	v_pk_mul_f32 v[4:5], v[130:131], v[4:5]
	v_add_f32_dpp v8, v8, v8 quad_perm:[2,3,0,1] row_mask:0xf bank_mask:0xf bound_ctrl:1
	v_pk_mul_f32 v[6:7], v[6:7], v[10:11]
	v_add_f32_e32 v4, 0, v4
	v_add_f32_dpp v8, v8, v8 row_half_mirror row_mask:0xf bank_mask:0xf bound_ctrl:1
	v_pk_mul_f32 v[6:7], v[132:133], v[6:7]
	v_add_f32_e32 v4, v5, v4
	v_add_f32_dpp v5, v8, v8 row_mirror row_mask:0xf bank_mask:0xf bound_ctrl:1
	v_add_f32_e32 v6, v6, v4
	v_mul_f32_e32 v4, 0x3c800000, v5
	v_add_f32_e32 v8, v7, v6
	v_pk_add_f32 v[6:7], v[122:123], v[4:5] op_sel_hi:[1,0] neg_lo:[0,1] neg_hi:[0,1]
	v_pk_add_f32 v[4:5], v[124:125], v[4:5] op_sel_hi:[1,0] neg_lo:[0,1] neg_hi:[0,1]
	v_add_f32_dpp v17, v8, v8 quad_perm:[1,0,3,2] row_mask:0xf bank_mask:0xf bound_ctrl:1
	v_pk_mul_f32 v[8:9], v[6:7], v[6:7]
	v_pk_mul_f32 v[10:11], v[4:5], v[4:5]
	v_add_f32_e32 v8, v8, v9
	v_add_f32_e32 v8, v10, v8
	v_add_f32_e32 v8, v11, v8
	v_add_f32_dpp v17, v17, v17 quad_perm:[2,3,0,1] row_mask:0xf bank_mask:0xf bound_ctrl:1
	v_mov_b32_e32 v112, v16
	v_add_f32_dpp v8, v8, v8 quad_perm:[1,0,3,2] row_mask:0xf bank_mask:0xf bound_ctrl:1
	v_mov_b32_e32 v16, v18
	v_mov_b32_e32 v149, v20
	v_add_f32_dpp v8, v8, v8 quad_perm:[2,3,0,1] row_mask:0xf bank_mask:0xf bound_ctrl:1
	s_nop 1
	v_add_f32_dpp v8, v8, v8 row_half_mirror row_mask:0xf bank_mask:0xf bound_ctrl:1
	s_nop 1
	v_add_f32_dpp v8, v8, v8 row_mirror row_mask:0xf bank_mask:0xf bound_ctrl:1
	v_fmamk_f32 v8, v8, 0x3c800000, v108
	v_mul_f32_e32 v9, 0x4b800000, v8
	v_cmp_gt_f32_e32 vcc, s26, v8
	s_nop 1
	v_cndmask_b32_e32 v8, v8, v9, vcc
	v_rsq_f32_e32 v8, v8
	v_add_f32_dpp v9, v17, v17 row_half_mirror row_mask:0xf bank_mask:0xf bound_ctrl:1
	v_mov_b32_e32 v17, v14
	v_mov_b32_e32 v14, v19
	v_mov_b32_dpp v10, v9 row_mirror row_mask:0xf bank_mask:0xf bound_ctrl:1
	v_add_f32_e32 v18, v9, v10
	v_mul_f32_e32 v9, 0x45800000, v8
	v_cndmask_b32_e32 v141, v8, v9, vcc
	v_pk_add_f32 v[0:1], v[0:1], v[140:141] neg_lo:[0,1] neg_hi:[0,1]
	v_pk_mul_f32 v[8:9], v[6:7], v[140:141] op_sel_hi:[0,1]
	v_mov_b32_e32 v143, v141
	v_mov_b32_e32 v1, v9
	v_pk_add_f32 v[8:9], v[26:27], v[142:143] neg_lo:[0,1] neg_hi:[0,1]
	v_pk_mul_f32 v[6:7], v[6:7], v[142:143]
	v_pk_fma_f32 v[0:1], v[0:1], v[112:113], v[148:149]
	v_mov_b32_e32 v145, v141
	v_mov_b32_e32 v143, v21
	v_mov_b32_e32 v9, v7
	v_fmac_f32_e32 v1, v0, v18
	v_mov_b32_e32 v0, v3
	v_mov_b32_e32 v105, v141
	v_pk_add_f32 v[10:11], v[2:3], v[144:145] neg_lo:[0,1] neg_hi:[0,1]
	v_pk_mul_f32 v[20:21], v[4:5], v[144:145] op_sel_hi:[0,1]
	v_pk_fma_f32 v[6:7], v[8:9], v[12:13], v[142:143]
	v_pk_add_f32 v[2:3], v[0:1], v[104:105] neg_lo:[0,1] neg_hi:[0,1]
	s_waitcnt vmcnt(3)
	v_lshlrev_b32_e32 v0, 16, v146
	v_mov_b32_e32 v11, v21
	v_fmac_f32_e32 v7, v6, v18
	v_mov_b32_e32 v145, v22
	v_pk_mul_f32 v[4:5], v[4:5], v[104:105]
	v_mul_f32_e32 v0, v1, v0
	v_and_b32_e32 v1, 0xffff0000, v146
	v_pk_fma_f32 v[8:9], v[10:11], v[16:17], v[144:145]
	v_mov_b32_e32 v3, v5
	v_mov_b32_e32 v105, v23
	v_mul_f32_e32 v1, v7, v1
	v_fmac_f32_e32 v9, v8, v18
	v_pk_fma_f32 v[2:3], v[2:3], v[14:15], v[104:105]
	v_cvt_pk_bf16_f32 v0, v0, v1
	v_lshlrev_b32_e32 v1, 16, v147
	v_fmac_f32_e32 v3, v2, v18
	v_mul_f32_e32 v1, v9, v1
	v_and_b32_e32 v2, 0xffff0000, v147
	v_mul_f32_e32 v2, v3, v2
	v_cvt_pk_bf16_f32 v1, v1, v2
	global_store_dwordx2 v[90:91], v[0:1], off offset:2304
	s_and_saveexec_b64 s[4:5], s[6:7]
	s_xor_b64 s[6:7], exec, s[4:5]
	s_cbranch_execz .LBB0_4250
; __device__ __forceinline__ float lo_bf(unsigned w) { return __uint_as_float(w << 16); }
; __device__ __forceinline__ float hi_bf(unsigned w) { return __uint_as_float(w & 0xffff0000u); }
; __device__ __forceinline__ void rwkv_post_rows(const Params& P, int l, int rbeg, int rend) {
;     ...
;             if (!first) {
;                 const u32x2 dr = *(const u32x2*)(p - NIN), dk = *(const u32x2*)(p + 1024 - NIN), dv = *(const u32x2*)(p + 2048 - NIN);
;                 qr[0] = lo_bf(dr.x); qr[1] = hi_bf(dr.x); qr[2] = lo_bf(dr.y); qr[3] = hi_bf(dr.y);
;                 qk[0] = lo_bf(dk.x); qk[1] = hi_bf(dk.x); qk[2] = lo_bf(dk.y); qk[3] = hi_bf(dk.y);
;                 qv[0] = lo_bf(dv.x); qv[1] = hi_bf(dv.x); qv[2] = lo_bf(dv.y); qv[3] = hi_bf(dv.y);
	v_add_co_u32_e32 v0, vcc, 0xe07e000, v92
	s_nop 1
	v_addc_co_u32_e32 v1, vcc, 0, v93, vcc
	v_add_co_u32_e32 v2, vcc, 0xe07f000, v92
	global_load_dwordx2 v[0:1], v[0:1], off offset:2304
	s_nop 0
	v_addc_co_u32_e32 v3, vcc, 0, v93, vcc
	global_load_dwordx2 v[10:11], v[2:3], off offset:256
	global_load_dwordx2 v[12:13], v[2:3], off offset:2304
	s_waitcnt vmcnt(2)
	v_lshlrev_b32_e32 v4, 16, v0
	v_and_b32_e32 v5, 0xffff0000, v0
	v_lshlrev_b32_e32 v6, 16, v1
	v_and_b32_e32 v7, 0xffff0000, v1
	s_waitcnt vmcnt(1)
	v_lshlrev_b32_e32 v8, 16, v10
	v_and_b32_e32 v9, 0xffff0000, v10
	v_lshlrev_b32_e32 v10, 16, v11
	v_and_b32_e32 v11, 0xffff0000, v11
	s_waitcnt vmcnt(0)
	v_lshlrev_b32_e32 v0, 16, v12
	v_and_b32_e32 v1, 0xffff0000, v12
	v_lshlrev_b32_e32 v2, 16, v13
	v_and_b32_e32 v3, 0xffff0000, v13
